# selfmax removal + softmax max folded into QK MFMA C-init (both softmaxes, both attention loops)
# speedup vs baseline: 1.0080x; 1.0080x over previous
.LBB0_552:
	s_waitcnt vmcnt(38)
	v_mov_b32_e32 v24, v0
	s_ashr_i32 s0, s56, 6
	s_and_b32 s57, s56, 15
	v_readfirstlane_b32 s1, v24
	s_ashr_i32 s5, s1, 6
	s_waitcnt vmcnt(37)
	v_and_b32_e32 v26, 15, v24
	s_ashr_i32 s1, s0, 31
	s_lshl_b64 s[88:89], s[0:1], 12
	v_lshl_or_b32 v200, s5, 4, v26
	s_lshl_b32 s4, s57, 7
	s_or_b32 s6, s88, s4
	s_mov_b32 s7, s89
	v_ashrrev_i32_e32 v201, 31, v200
	v_lshl_add_u64 v[198:199], s[6:7], 0, v[200:201]
	s_lshl_b32 s4, s56, 3
	v_lshlrev_b64 v[4:5], 10, v[198:199]
	s_and_b32 s54, s4, 0x180
	v_bfe_u32 v25, v24, 4, 2
	v_lshl_add_u64 v[4:5], s[64:65], 0, v[4:5]
	s_lshl_b32 s94, s54, 1
	v_ashrrev_i32_e32 v22, 4, v24
	v_lshl_add_u64 v[4:5], v[4:5], 0, s[94:95]
	v_lshlrev_b32_e32 v2, 4, v25
	v_ashrrev_i32_e32 v23, 31, v22
	v_lshl_add_u64 v[20:21], v[4:5], 0, v[2:3]
	v_lshl_add_u64 v[4:5], s[88:89], 0, v[22:23]
	v_lshlrev_b64 v[4:5], 10, v[4:5]
	v_lshl_add_u64 v[6:7], s[68:69], 0, v[4:5]
	v_lshl_add_u64 v[4:5], s[66:67], 0, v[4:5]
	v_lshlrev_b32_e32 v2, 4, v26
	v_lshl_add_u64 v[4:5], v[4:5], 0, s[94:95]
	v_lshl_add_u64 v[8:9], v[4:5], 0, v[2:3]
	s_mov_b32 s4, 0x8000
	v_lshl_add_u64 v[6:7], v[6:7], 0, s[94:95]
	v_add_co_u32_e32 v4, vcc, s4, v8
	v_lshl_add_u64 v[16:17], v[6:7], 0, v[2:3]
	s_nop 0
	v_addc_co_u32_e32 v5, vcc, 0, v9, vcc
	global_load_dwordx4 v[4:7], v[4:5], off
	s_nop 0
	global_load_dwordx4 v[8:11], v[8:9], off
	s_nop 0
	global_load_dwordx4 v[12:15], v[16:17], off
	v_add_co_u32_e32 v16, vcc, s4, v16
	v_lshrrev_b32_e32 v27, 4, v24
	s_nop 0
	v_addc_co_u32_e32 v17, vcc, 0, v17, vcc
	global_load_dwordx4 v[16:19], v[16:17], off
	s_nop 0
	global_load_dwordx4 v[80:83], v[20:21], off
	global_load_dwordx4 v[68:71], v[20:21], off offset:64
	global_load_dwordx4 v[76:79], v[20:21], off offset:128
	global_load_dwordx4 v[72:75], v[20:21], off offset:192
	v_lshlrev_b32_e32 v29, 8, v26
	v_bitop3_b32 v27, v27, v26, 3 bitop3:0x6c
	v_lshl_or_b32 v217, v27, 4, v29
	v_bitop3_b32 v27, v25, v26, 4 bitop3:0x36
	v_xor_b32_e32 v20, v22, v24
	v_lshl_or_b32 v218, v27, 4, v29
	v_bitop3_b32 v27, v25, v26, 8 bitop3:0x36
	v_bitop3_b32 v26, v25, v26, 12 bitop3:0x36
	v_lshlrev_b32_e32 v20, 4, v20
	v_lshl_or_b32 v216, v26, 4, v29
	v_lshlrev_b32_e32 v26, 8, v22
	v_bfe_u32 v21, v24, 1, 3
	v_lshlrev_b32_e32 v28, 4, v24
	v_and_or_b32 v219, v20, s2, v26
	v_bfe_u32 v20, v24, 2, 2
	v_lshlrev_b32_e32 v201, 2, v25
	v_lshlrev_b32_e32 v24, 3, v24
	v_bitop3_b32 v21, v21, v22, 7 bitop3:0x78
	v_or_b32_e32 v20, v201, v20
	v_and_b32_e32 v24, 24, v24
	v_lshlrev_b32_e32 v21, 5, v21
	v_and_b32_e32 v28, 16, v28
	v_lshl_or_b32 v24, v20, 8, v24
	v_lshlrev_b32_e32 v20, 5, v20
	v_and_b32_e32 v25, 0xe0, v20
	v_bitop3_b32 v205, v20, s59, v24 bitop3:0x26
	v_or3_b32 v220, v21, v28, v26
	v_add_u32_e32 v20, 0, v219
	s_lshl_b32 s4, s96, 1
	s_movk_i32 s9, 0x80
	s_lshl_b64 s[82:83], s[0:1], 22
	s_and_b32 s58, s4, 0x300
	v_bitop3_b32 v208, v25, s9, v24 bitop3:0x36
	s_movk_i32 s9, 0xa0
	v_bitop3_b32 v207, v25, s9, v24 bitop3:0x36
	s_movk_i32 s9, 0xc0
	s_and_b32 s6, s97, 15
	v_lshl_or_b32 v215, v27, 4, v29
	v_or_b32_e32 v214, v25, v24
	v_bitop3_b32 v213, v25, 32, v24 bitop3:0x36
	v_bitop3_b32 v212, v25, 64, v24 bitop3:0x36
	v_bitop3_b32 v211, v25, s71, v24 bitop3:0x36
	v_bitop3_b32 v206, v25, s9, v24 bitop3:0x36
	v_mov_b32_e32 v21, v3
	v_mov_b32_e32 v24, v3
	v_mov_b32_e32 v25, v3
	v_mov_b32_e32 v26, v3
	s_waitcnt vmcnt(6)
	ds_write_b128 v20, v[8:11]
	ds_write_b128 v20, v[4:7] offset:8192
	v_add_u32_e32 v4, 0, v220
	s_waitcnt vmcnt(5)
	ds_write_b128 v4, v[12:15] offset:16384
	s_waitcnt vmcnt(4)
	ds_write_b128 v4, v[16:19] offset:24576
	v_lshlrev_b64 v[4:5], 10, v[22:23]
	v_lshl_add_u64 v[4:5], s[82:83], 0, v[4:5]
	v_or3_b32 v4, v4, s58, v2
	v_lshl_add_u64 v[202:203], s[90:91], 0, v[4:5]
	v_mov_b32_e32 v4, v3
	v_mov_b32_e32 v5, v3
	v_mov_b32_e32 v6, v3
	v_mov_b32_e32 v7, v3
	v_mov_b32_e32 v8, v3
	v_mov_b32_e32 v9, v3
	v_mov_b32_e32 v10, v3
	v_mov_b32_e32 v11, v3
	v_mov_b32_e32 v12, v3
	v_mov_b32_e32 v13, v3
	v_mov_b32_e32 v14, v3
	v_mov_b32_e32 v15, v3
	v_mov_b32_e32 v16, v3
	v_mov_b32_e32 v17, v3
	v_mov_b32_e32 v18, v3
	v_mov_b32_e32 v19, v3
	v_mov_b32_e32 v20, v3
	v_mov_b32_e32 v22, v3
	v_mov_b32_e32 v23, v3
	v_mov_b32_e32 v27, v3
	v_mov_b32_e32 v28, v3
	v_mov_b32_e32 v29, v3
	v_mov_b32_e32 v30, v3
	v_mov_b32_e32 v31, v3
	v_mov_b32_e32 v32, v3
	v_mov_b32_e32 v33, v3
	v_mov_b32_e32 v38, v3
	v_mov_b32_e32 v39, v3
	s_lshl_b32 s4, s6, 7
	v_mov_b32_e32 v2, v3
	v_mov_b32_e32 v36, v3
	v_mov_b32_e32 v37, v3
	v_mov_b64_e32 v[42:43], v[38:39]
	v_mov_b64_e32 v[46:47], v[38:39]
	v_mov_b64_e32 v[50:51], v[38:39]
	v_mov_b64_e32 v[54:55], v[38:39]
	v_mov_b64_e32 v[58:59], v[38:39]
	v_mov_b64_e32 v[62:63], v[38:39]
	v_mov_b64_e32 v[66:67], v[38:39]
	v_mov_b64_e32 v[34:35], v[32:33]
	s_mov_b32 s7, 0
	s_sub_i32 s8, 0, s4
	s_lshl_b32 s4, s57, 1
	v_mov_b32_e32 v230, 0xf149f2ca
	s_mov_b32 s0, 0x8000
	v_mov_b64_e32 v[40:41], v[36:37]
	v_mov_b64_e32 v[44:45], v[36:37]
	v_mov_b64_e32 v[48:49], v[36:37]
	v_mov_b64_e32 v[52:53], v[36:37]
	v_mov_b64_e32 v[56:57], v[36:37]
	v_mov_b64_e32 v[60:61], v[36:37]
	v_mov_b64_e32 v[64:65], v[36:37]
	v_mov_b64_e32 v[32:33], v[30:31]
	v_mov_b64_e32 v[30:31], v[28:29]
	v_mov_b64_e32 v[28:29], v[26:27]
	v_mov_b64_e32 v[26:27], v[24:25]
	v_mov_b64_e32 v[24:25], v[22:23]
	v_mov_b64_e32 v[22:23], v[20:21]
	v_mov_b64_e32 v[20:21], v[18:19]
	v_mov_b64_e32 v[18:19], v[16:17]
	v_mov_b64_e32 v[16:17], v[14:15]
	v_mov_b64_e32 v[14:15], v[12:13]
	v_mov_b64_e32 v[12:13], v[10:11]
	v_mov_b64_e32 v[10:11], v[8:9]
	v_mov_b64_e32 v[8:9], v[6:7]
	v_mov_b64_e32 v[6:7], v[4:5]
	v_mov_b64_e32 v[4:5], v[2:3]
	v_mov_b32_e32 v228, 0
	v_mov_b32_e32 v229, 0
	v_mov_b32_e32 v204, 0xf149f2ca
	s_waitcnt lgkmcnt(0)
	s_barrier
	v_mov_b32_e32 v246, 0
	v_mov_b32_e32 v247, 0
	v_mov_b32_e32 v248, 0
	v_mov_b32_e32 v249, 0
	v_mov_b32_e32 v250, 0
	v_mov_b32_e32 v251, 0
	v_mov_b32_e32 v252, 0
	v_mov_b32_e32 v253, 0
.LBB0_553:
	s_mov_b32 s9, 0xfeef8000
	v_add_co_u32_e32 v84, vcc, s9, v202
	s_mov_b32 s9, 0xfef00000
	s_nop 0
	v_addc_co_u32_e32 v85, vcc, -1, v203, vcc
	v_add_co_u32_e32 v88, vcc, s9, v202
	s_movk_i32 s9, 0x8000
	s_nop 0
	v_addc_co_u32_e32 v89, vcc, -1, v203, vcc
	v_add_co_u32_e32 v92, vcc, s9, v202
	global_load_dwordx4 v[84:87], v[84:85], off
	s_nop 0
	v_addc_co_u32_e32 v93, vcc, -1, v203, vcc
	global_load_dwordx4 v[88:91], v[88:89], off
	s_nop 0
	global_load_dwordx4 v[92:95], v[92:93], off
	s_nop 0
	global_load_dwordx4 v[96:99], v[202:203], off
	s_add_i32 s1, s0, 0xffff8000
	s_and_b32 s1, s1, 0x8000
	s_add_i32 s1, s1, 0
	v_add_u32_e32 v156, s1, v215
	ds_read_b128 v[108:111], v156
	v_add_u32_e32 v2, s1, v217
	v_add_u32_e32 v152, s1, v218
	v_add_u32_e32 v160, s1, v216
	ds_read_b128 v[100:103], v2
	ds_read_b128 v[104:107], v152
	ds_read_b128 v[112:115], v160
	ds_read_b128 v[116:119], v2 offset:4096
	ds_read_b128 v[120:123], v152 offset:4096
	ds_read_b128 v[124:127], v156 offset:4096
	ds_read_b128 v[128:131], v160 offset:4096
	ds_read_b128 v[132:135], v2 offset:8192
	ds_read_b128 v[136:139], v152 offset:8192
	ds_read_b128 v[140:143], v156 offset:8192
	ds_read_b128 v[144:147], v160 offset:8192
	ds_read_b128 v[148:151], v2 offset:12288
	ds_read_b128 v[152:155], v152 offset:12288
	ds_read_b128 v[156:159], v156 offset:12288
	ds_read_b128 v[160:163], v160 offset:12288
	s_waitcnt vmcnt(5) lgkmcnt(14)
	v_mfma_f32_16x16x32_bf16 v[108:111], v[108:111], v[76:79], v[250:253]
	v_add_u32_e32 v2, s1, v214
	s_cmp_lt_u32 s7, s4
	s_waitcnt lgkmcnt(1)
	v_mfma_f32_16x16x32_bf16 v[156:159], v[156:159], v[76:79], v[250:253]
	v_mfma_f32_16x16x32_bf16 v[116:119], v[116:119], v[80:83], v[246:249]
	v_mfma_f32_16x16x32_bf16 v[124:127], v[124:127], v[76:79], v[250:253]
	v_mfma_f32_16x16x32_bf16 v[148:151], v[148:151], v[80:83], v[246:249]
	v_mfma_f32_16x16x32_bf16 v[140:143], v[140:143], v[76:79], v[250:253]
	s_waitcnt vmcnt(4)
	v_mfma_f32_16x16x32_bf16 v[168:171], v[112:115], v[72:75], v[108:111]
	s_waitcnt lgkmcnt(0)
	v_mfma_f32_16x16x32_bf16 v[176:179], v[160:163], v[72:75], v[156:159]
	s_nop 2
	ds_read_b64_tr_b16 v[156:157], v2 offset:16384
	ds_read_b64_tr_b16 v[158:159], v2 offset:20480
	ds_read_b64_tr_b16 v[112:113], v2 offset:24576
	ds_read_b64_tr_b16 v[114:115], v2 offset:28672
	v_add_u32_e32 v2, s1, v213
	v_mfma_f32_16x16x32_bf16 v[184:187], v[120:123], v[68:71], v[116:119]
	ds_read_b64_tr_b16 v[160:161], v2 offset:16384
	ds_read_b64_tr_b16 v[162:163], v2 offset:20480
	s_nop 0
	ds_read_b64_tr_b16 v[116:117], v2 offset:24576
	ds_read_b64_tr_b16 v[118:119], v2 offset:28672
	v_add_u32_e32 v2, s1, v212
	v_mfma_f32_16x16x32_bf16 v[100:103], v[100:103], v[80:83], v[246:249]
	v_mfma_f32_16x16x32_bf16 v[132:135], v[132:135], v[80:83], v[246:249]
	v_mfma_f32_16x16x32_bf16 v[172:175], v[128:131], v[72:75], v[124:127]
	v_mfma_f32_16x16x32_bf16 v[188:191], v[152:155], v[68:71], v[148:151]
	ds_read_b64_tr_b16 v[152:153], v2 offset:16384
	ds_read_b64_tr_b16 v[154:155], v2 offset:20480
	ds_read_b64_tr_b16 v[124:125], v2 offset:24576
	ds_read_b64_tr_b16 v[126:127], v2 offset:28672
	v_add_u32_e32 v2, s1, v211
	ds_read_b64_tr_b16 v[148:149], v2 offset:16384
	ds_read_b64_tr_b16 v[150:151], v2 offset:20480
	ds_read_b64_tr_b16 v[128:129], v2 offset:24576
	ds_read_b64_tr_b16 v[130:131], v2 offset:28672
	v_add_u32_e32 v2, s1, v208
	v_mfma_f32_16x16x32_bf16 v[180:183], v[144:147], v[72:75], v[140:143]
	ds_read_b64_tr_b16 v[144:145], v2 offset:16384
	ds_read_b64_tr_b16 v[146:147], v2 offset:20480
	ds_read_b64_tr_b16 v[120:121], v2 offset:24576
	ds_read_b64_tr_b16 v[122:123], v2 offset:28672
	v_add_u32_e32 v2, s1, v207
	ds_read_b64_tr_b16 v[140:141], v2 offset:16384
	ds_read_b64_tr_b16 v[142:143], v2 offset:20480
	ds_read_b64_tr_b16 v[108:109], v2 offset:24576
	ds_read_b64_tr_b16 v[110:111], v2 offset:28672
	v_add_u32_e32 v2, s1, v206
	v_mfma_f32_16x16x32_bf16 v[164:167], v[104:107], v[68:71], v[100:103]
	v_mfma_f32_16x16x32_bf16 v[192:195], v[136:139], v[68:71], v[132:135]
	ds_read_b64_tr_b16 v[136:137], v2 offset:16384
	ds_read_b64_tr_b16 v[138:139], v2 offset:20480
	ds_read_b64_tr_b16 v[104:105], v2 offset:24576
	ds_read_b64_tr_b16 v[106:107], v2 offset:28672
	v_add_u32_e32 v2, s1, v205
	ds_read_b64_tr_b16 v[132:133], v2 offset:16384
	ds_read_b64_tr_b16 v[134:135], v2 offset:20480
	ds_read_b64_tr_b16 v[100:101], v2 offset:24576
	ds_read_b64_tr_b16 v[102:103], v2 offset:28672
	s_cbranch_scc1 .LBB0_555
	v_add_u32_e32 v221, s8, v201
	v_mov_b32_e32 v2, s46
	v_mov_b32_e32 v232, s46
	v_cmp_gt_i32_e32 vcc, v221, v200
	s_nop 1
	v_cndmask_b32_e32 v2, v164, v2, vcc
	v_cndmask_b32_e32 v227, v168, v232, vcc
	v_cmp_lt_i32_e32 vcc, v221, v200
	s_nop 1
	v_cndmask_b32_e32 v164, v2, v164, vcc
	v_add_u32_e32 v2, 2, v221
	v_cndmask_b32_e32 v165, v210, v165, vcc
	v_cndmask_b32_e32 v168, v227, v168, vcc
	v_cndmask_b32_e32 v169, v210, v169, vcc
	v_cmp_gt_i32_e32 vcc, v2, v200
	v_add_u32_e32 v2, 3, v221
	v_add_u32_e32 v227, 16, v221
	v_cndmask_b32_e32 v166, v166, v210, vcc
	v_cndmask_b32_e32 v170, v170, v210, vcc
	v_cmp_gt_i32_e32 vcc, v2, v200
	v_mov_b32_e32 v2, s46
	s_nop 0
	v_cndmask_b32_e32 v167, v167, v210, vcc
	v_cndmask_b32_e32 v171, v171, v210, vcc
	v_cmp_gt_i32_e32 vcc, v227, v200
	v_add_u32_e32 v227, 32, v221
	s_nop 0
	v_cndmask_b32_e32 v184, v184, v2, vcc
	v_add_u32_e32 v2, 17, v221
	v_cndmask_b32_e32 v172, v172, v232, vcc
	v_cmp_gt_i32_e32 vcc, v2, v200
	v_add_u32_e32 v2, 18, v221
	s_nop 0
	v_cndmask_b32_e32 v185, v185, v210, vcc
	v_cndmask_b32_e32 v173, v173, v210, vcc
	v_cmp_gt_i32_e32 vcc, v2, v200
	v_add_u32_e32 v2, 19, v221
	s_nop 0
	v_cndmask_b32_e32 v186, v186, v210, vcc
	v_cndmask_b32_e32 v174, v174, v210, vcc
	v_cmp_gt_i32_e32 vcc, v2, v200
	v_mov_b32_e32 v2, s46
	s_nop 0
	v_cndmask_b32_e32 v187, v187, v210, vcc
	v_cndmask_b32_e32 v175, v175, v210, vcc
	v_cmp_gt_i32_e32 vcc, v227, v200
	v_add_u32_e32 v227, 48, v221
	s_nop 0
	v_cndmask_b32_e32 v192, v192, v2, vcc
	v_add_u32_e32 v2, 33, v221
	v_cndmask_b32_e32 v180, v180, v232, vcc
	v_cmp_gt_i32_e32 vcc, v2, v200
	v_add_u32_e32 v2, 34, v221
	s_nop 0
	v_cndmask_b32_e32 v193, v193, v210, vcc
	v_cndmask_b32_e32 v181, v181, v210, vcc
	v_cmp_gt_i32_e32 vcc, v2, v200
	v_add_u32_e32 v2, 35, v221
	s_nop 0
	v_cndmask_b32_e32 v194, v194, v210, vcc
	v_cndmask_b32_e32 v182, v182, v210, vcc
	v_cmp_gt_i32_e32 vcc, v2, v200
	v_mov_b32_e32 v2, s46
	s_nop 0
	v_cndmask_b32_e32 v195, v195, v210, vcc
	v_cndmask_b32_e32 v183, v183, v210, vcc
	v_cmp_gt_i32_e32 vcc, v227, v200
	s_nop 1
	v_cndmask_b32_e32 v188, v188, v2, vcc
	v_add_u32_e32 v2, 49, v221
	v_cndmask_b32_e32 v176, v176, v232, vcc
	v_cmp_gt_i32_e32 vcc, v2, v200
	v_add_u32_e32 v2, 50, v221
	s_nop 0
	v_cndmask_b32_e32 v189, v189, v210, vcc
	v_cndmask_b32_e32 v177, v177, v210, vcc
	v_cmp_gt_i32_e32 vcc, v2, v200
	v_add_u32_e32 v2, 51, v221
	s_nop 0
	v_cndmask_b32_e32 v190, v190, v210, vcc
	v_cndmask_b32_e32 v178, v178, v210, vcc
	v_cmp_gt_i32_e32 vcc, v2, v200
	s_nop 1
	v_cndmask_b32_e32 v191, v191, v210, vcc
	v_cndmask_b32_e32 v179, v179, v210, vcc
.LBB0_555:
	v_max_f32_e32 v2, v164, v165
	v_max_f32_e32 v221, v166, v167
	v_max_f32_e32 v227, v186, v187
	v_max3_f32 v227, v184, v185, v227
	v_max3_f32 v2, v2, v221, v227
	v_max_f32_e32 v221, v194, v195
	v_max_f32_e32 v231, v190, v190
	v_max_f32_e32 v227, v231, v191
	v_max3_f32 v221, v192, v193, v221
	v_max3_f32 v227, v188, v189, v227
	v_max3_f32 v2, v2, v221, v227
	v_mov_b32_e32 v221, v2
	s_nop 1
	v_permlane16_swap_b32_e32 v2, v221
	v_max_f32_e32 v2, v2, v221
	v_mov_b32_e32 v221, v2
	s_nop 1
	v_permlane32_swap_b32_e32 v2, v221
	v_max3_f32 v227, v230, v2, v221
	v_exp_f32_e64 v2, -v227
	s_nop 0
	v_cmp_neq_f32_e32 vcc, 1.0, v2
	s_cbranch_vccz .LBB0_557
	v_pk_mul_f32 v[34:35], v[34:35], v[2:3] op_sel_hi:[1,0]
	v_pk_mul_f32 v[32:33], v[32:33], v[2:3] op_sel_hi:[1,0]
	v_pk_mul_f32 v[30:31], v[30:31], v[2:3] op_sel_hi:[1,0]
	v_pk_mul_f32 v[28:29], v[28:29], v[2:3] op_sel_hi:[1,0]
	v_pk_mul_f32 v[26:27], v[26:27], v[2:3] op_sel_hi:[1,0]
	v_pk_mul_f32 v[24:25], v[24:25], v[2:3] op_sel_hi:[1,0]
	v_pk_mul_f32 v[22:23], v[22:23], v[2:3] op_sel_hi:[1,0]
	v_pk_mul_f32 v[20:21], v[20:21], v[2:3] op_sel_hi:[1,0]
	v_pk_mul_f32 v[18:19], v[18:19], v[2:3] op_sel_hi:[1,0]
	v_pk_mul_f32 v[16:17], v[16:17], v[2:3] op_sel_hi:[1,0]
	v_pk_mul_f32 v[14:15], v[14:15], v[2:3] op_sel_hi:[1,0]
	v_pk_mul_f32 v[12:13], v[12:13], v[2:3] op_sel_hi:[1,0]
	v_pk_mul_f32 v[10:11], v[10:11], v[2:3] op_sel_hi:[1,0]
	v_pk_mul_f32 v[8:9], v[8:9], v[2:3] op_sel_hi:[1,0]
	v_pk_mul_f32 v[6:7], v[6:7], v[2:3] op_sel_hi:[1,0]
	v_pk_mul_f32 v[4:5], v[4:5], v[2:3] op_sel_hi:[1,0]
	v_sub_f32_e32 v246, v246, v227
	v_sub_f32_e32 v247, v247, v227
	v_sub_f32_e32 v248, v248, v227
	v_sub_f32_e32 v249, v249, v227
	v_sub_f32_e32 v164, v164, v227
	v_sub_f32_e32 v165, v165, v227
	v_sub_f32_e32 v166, v166, v227
	v_sub_f32_e32 v167, v167, v227
	v_sub_f32_e32 v184, v184, v227
	v_sub_f32_e32 v185, v185, v227
	v_sub_f32_e32 v186, v186, v227
	v_sub_f32_e32 v187, v187, v227
	v_sub_f32_e32 v188, v188, v227
	v_sub_f32_e32 v189, v189, v227
	v_sub_f32_e32 v190, v190, v227
	v_sub_f32_e32 v191, v191, v227
	v_sub_f32_e32 v192, v192, v227
	v_sub_f32_e32 v193, v193, v227
	v_sub_f32_e32 v194, v194, v227
	v_sub_f32_e32 v195, v195, v227
.LBB0_557:
	v_max_f32_e32 v221, v168, v169
	v_max_f32_e32 v230, v170, v171
	v_max_f32_e32 v231, v174, v175
	v_max3_f32 v231, v172, v173, v231
	v_max3_f32 v221, v221, v230, v231
	v_max_f32_e32 v230, v182, v183
	v_max_f32_e32 v232, v178, v178
	v_max_f32_e32 v231, v232, v179
	v_max3_f32 v230, v180, v181, v230
	v_max3_f32 v231, v176, v177, v231
	v_max3_f32 v221, v221, v230, v231
	v_mov_b32_e32 v230, v221
	s_nop 1
	v_permlane16_swap_b32_e32 v221, v230
	v_max_f32_e32 v221, v221, v230
	v_mov_b32_e32 v230, v221
	s_nop 1
	v_permlane32_swap_b32_e32 v221, v230
	v_max3_f32 v221, v204, v221, v230
	v_exp_f32_e64 v204, -v221
	s_nop 0
	v_cmp_neq_f32_e32 vcc, 1.0, v204
	s_cbranch_vccz .LBB0_559
	v_pk_mul_f32 v[66:67], v[66:67], v[204:205] op_sel_hi:[1,0]
	v_pk_mul_f32 v[64:65], v[64:65], v[204:205] op_sel_hi:[1,0]
	v_pk_mul_f32 v[62:63], v[62:63], v[204:205] op_sel_hi:[1,0]
	v_pk_mul_f32 v[60:61], v[60:61], v[204:205] op_sel_hi:[1,0]
	v_pk_mul_f32 v[58:59], v[58:59], v[204:205] op_sel_hi:[1,0]
	v_pk_mul_f32 v[56:57], v[56:57], v[204:205] op_sel_hi:[1,0]
	v_pk_mul_f32 v[54:55], v[54:55], v[204:205] op_sel_hi:[1,0]
	v_pk_mul_f32 v[52:53], v[52:53], v[204:205] op_sel_hi:[1,0]
	v_pk_mul_f32 v[50:51], v[50:51], v[204:205] op_sel_hi:[1,0]
	v_pk_mul_f32 v[48:49], v[48:49], v[204:205] op_sel_hi:[1,0]
	v_pk_mul_f32 v[46:47], v[46:47], v[204:205] op_sel_hi:[1,0]
	v_pk_mul_f32 v[44:45], v[44:45], v[204:205] op_sel_hi:[1,0]
	v_pk_mul_f32 v[42:43], v[42:43], v[204:205] op_sel_hi:[1,0]
	v_pk_mul_f32 v[40:41], v[40:41], v[204:205] op_sel_hi:[1,0]
	v_pk_mul_f32 v[38:39], v[38:39], v[204:205] op_sel_hi:[1,0]
	v_pk_mul_f32 v[36:37], v[36:37], v[204:205] op_sel_hi:[1,0]
	v_sub_f32_e32 v250, v250, v221
	v_sub_f32_e32 v251, v251, v221
	v_sub_f32_e32 v252, v252, v221
	v_sub_f32_e32 v253, v253, v221
	v_sub_f32_e32 v168, v168, v221
	v_sub_f32_e32 v169, v169, v221
	v_sub_f32_e32 v170, v170, v221
	v_sub_f32_e32 v171, v171, v221
	v_sub_f32_e32 v172, v172, v221
	v_sub_f32_e32 v173, v173, v221
	v_sub_f32_e32 v174, v174, v221
	v_sub_f32_e32 v175, v175, v221
	v_sub_f32_e32 v176, v176, v221
	v_sub_f32_e32 v177, v177, v221
	v_sub_f32_e32 v178, v178, v221
	v_sub_f32_e32 v179, v179, v221
	v_sub_f32_e32 v180, v180, v221
	v_sub_f32_e32 v181, v181, v221
	v_sub_f32_e32 v182, v182, v221
	v_sub_f32_e32 v183, v183, v221
.LBB0_559:
	v_exp_f32_e32 v230, v164
	v_exp_f32_e32 v231, v165
	v_exp_f32_e32 v232, v166
	v_exp_f32_e32 v233, v167
	v_exp_f32_e32 v234, v184
	v_exp_f32_e32 v235, v185
	v_exp_f32_e32 v236, v186
	v_exp_f32_e32 v237, v187
	v_exp_f32_e32 v192, v192
	v_exp_f32_e32 v193, v193
	v_exp_f32_e32 v194, v194
	v_exp_f32_e32 v195, v195
	v_exp_f32_e32 v168, v168
	v_exp_f32_e32 v169, v169
	v_exp_f32_e32 v170, v170
	v_exp_f32_e32 v171, v171
	v_exp_f32_e32 v172, v172
	v_exp_f32_e32 v173, v173
	v_exp_f32_e32 v174, v174
	v_exp_f32_e32 v175, v175
	v_exp_f32_e32 v180, v180
	v_exp_f32_e32 v181, v181
	v_exp_f32_e32 v182, v182
	v_exp_f32_e32 v183, v183
	v_exp_f32_e32 v176, v176
	v_exp_f32_e32 v177, v177
	v_exp_f32_e32 v178, v178
	v_exp_f32_e32 v179, v179
	v_exp_f32_e32 v238, v190
	v_exp_f32_e32 v239, v191
	v_exp_f32_e32 v190, v188
	v_exp_f32_e32 v191, v189
	v_pk_add_f32 v[188:189], v[168:169], v[172:173]
	v_pk_add_f32 v[240:241], v[170:171], v[174:175]
	v_pk_add_f32 v[242:243], v[180:181], v[176:177]
	v_pk_add_f32 v[244:245], v[182:183], v[178:179]
	v_cvt_pk_bf16_f32 v184, v230, v231
	v_cvt_pk_bf16_f32 v185, v232, v233
	v_cvt_pk_bf16_f32 v164, v192, v193
	v_cvt_pk_bf16_f32 v166, v190, v191
	v_pk_add_f32 v[240:241], v[240:241], v[244:245]
	v_pk_add_f32 v[188:189], v[188:189], v[242:243]
	v_pk_add_f32 v[230:231], v[230:231], v[234:235]
	v_pk_add_f32 v[232:233], v[232:233], v[236:237]
	v_pk_add_f32 v[190:191], v[192:193], v[190:191]
	v_pk_add_f32 v[192:193], v[194:195], v[238:239]
	v_add_f32_e32 v188, v188, v189
	v_add_f32_e32 v189, v240, v241
	v_pk_add_f32 v[192:193], v[232:233], v[192:193]
	v_pk_add_f32 v[190:191], v[230:231], v[190:191]
	v_add_f32_e32 v188, v188, v189
	v_add_f32_e32 v189, v190, v191
	v_add_f32_e32 v190, v192, v193
	v_cvt_pk_bf16_f32 v186, v234, v235
	v_cvt_pk_bf16_f32 v187, v236, v237
	v_add_f32_e32 v189, v189, v190
	v_cvt_pk_bf16_f32 v190, v168, v169
	v_cvt_pk_bf16_f32 v191, v170, v171
	v_cvt_pk_bf16_f32 v192, v172, v173
	v_cvt_pk_bf16_f32 v193, v174, v175
	s_waitcnt lgkmcnt(14)
	v_mfma_f32_16x16x32_bf16 v[4:7], v[156:159], v[184:187], v[4:7]
	v_cvt_pk_bf16_f32 v165, v194, v195
	v_cvt_pk_bf16_f32 v167, v238, v239
	v_cvt_pk_bf16_f32 v168, v180, v181
	v_mfma_f32_16x16x32_bf16 v[64:67], v[156:159], v[190:193], v[64:67]
	v_cvt_pk_bf16_f32 v169, v182, v183
	v_cvt_pk_bf16_f32 v170, v176, v177
	v_cvt_pk_bf16_f32 v171, v178, v179
	v_mfma_f32_16x16x32_bf16 v[8:11], v[160:163], v[184:187], v[8:11]
	s_and_b32 s1, s0, 0x8000
	s_add_i32 s1, s1, 0
	s_add_i32 s8, s8, 64
	v_mfma_f32_16x16x32_bf16 v[60:63], v[160:163], v[190:193], v[60:63]
	s_add_i32 s0, s0, 0x8000
	s_mov_b64 s[10:11], 0x10000
	s_add_i32 s7, s7, 1
	v_mfma_f32_16x16x32_bf16 v[12:15], v[152:155], v[184:187], v[12:15]
	v_fmac_f32_e32 v188, v229, v204
	v_fmac_f32_e32 v189, v228, v2
	v_lshl_add_u64 v[202:203], v[202:203], 0, s[10:11]
	v_mfma_f32_16x16x32_bf16 v[56:59], v[152:155], v[190:193], v[56:59]
	s_cmp_eq_u32 s8, 64
	v_add_u32_e32 v2, s1, v220
	v_mfma_f32_16x16x32_bf16 v[16:19], v[148:151], v[184:187], v[16:19]
	v_mfma_f32_16x16x32_bf16 v[52:55], v[148:151], v[190:193], v[52:55]
	v_mfma_f32_16x16x32_bf16 v[20:23], v[144:147], v[184:187], v[20:23]
	v_mfma_f32_16x16x32_bf16 v[48:51], v[144:147], v[190:193], v[48:51]
	s_waitcnt lgkmcnt(10)
	v_mfma_f32_16x16x32_bf16 v[24:27], v[140:143], v[184:187], v[24:27]
	v_mfma_f32_16x16x32_bf16 v[44:47], v[140:143], v[190:193], v[44:47]
	s_waitcnt lgkmcnt(6)
	v_mfma_f32_16x16x32_bf16 v[28:31], v[136:139], v[184:187], v[28:31]
	v_mfma_f32_16x16x32_bf16 v[40:43], v[136:139], v[190:193], v[40:43]
	s_waitcnt lgkmcnt(2)
	v_mfma_f32_16x16x32_bf16 v[32:35], v[132:135], v[184:187], v[32:35]
	v_mfma_f32_16x16x32_bf16 v[36:39], v[132:135], v[190:193], v[36:39]
	v_mfma_f32_16x16x32_bf16 v[4:7], v[112:115], v[164:167], v[4:7]
	v_mfma_f32_16x16x32_bf16 v[64:67], v[112:115], v[168:171], v[64:67]
	v_mfma_f32_16x16x32_bf16 v[8:11], v[116:119], v[164:167], v[8:11]
	v_mfma_f32_16x16x32_bf16 v[60:63], v[116:119], v[168:171], v[60:63]
	v_mfma_f32_16x16x32_bf16 v[12:15], v[124:127], v[164:167], v[12:15]
	v_mfma_f32_16x16x32_bf16 v[56:59], v[124:127], v[168:171], v[56:59]
	v_mfma_f32_16x16x32_bf16 v[16:19], v[128:131], v[164:167], v[16:19]
	v_mfma_f32_16x16x32_bf16 v[52:55], v[128:131], v[168:171], v[52:55]
	v_mfma_f32_16x16x32_bf16 v[20:23], v[120:123], v[164:167], v[20:23]
	v_mfma_f32_16x16x32_bf16 v[48:51], v[120:123], v[168:171], v[48:51]
	v_mfma_f32_16x16x32_bf16 v[24:27], v[108:111], v[164:167], v[24:27]
	v_mfma_f32_16x16x32_bf16 v[44:47], v[108:111], v[168:171], v[44:47]
	v_mfma_f32_16x16x32_bf16 v[28:31], v[104:107], v[164:167], v[28:31]
	v_mfma_f32_16x16x32_bf16 v[40:43], v[104:107], v[168:171], v[40:43]
	s_waitcnt lgkmcnt(0)
	v_mfma_f32_16x16x32_bf16 v[32:35], v[100:103], v[164:167], v[32:35]
	v_mfma_f32_16x16x32_bf16 v[36:39], v[100:103], v[168:171], v[36:39]
	v_add_u32_e32 v100, s1, v219
	s_waitcnt vmcnt(3)
	ds_write_b128 v100, v[84:87]
	s_waitcnt vmcnt(2)
	ds_write_b128 v100, v[88:91] offset:8192
	s_waitcnt vmcnt(1)
	ds_write_b128 v2, v[92:95] offset:16384
	s_waitcnt vmcnt(0)
	ds_write_b128 v2, v[96:99] offset:24576
	s_waitcnt lgkmcnt(0)
	s_barrier
	s_cbranch_scc1 .LBB0_561
	v_mov_b32_e32 v228, v189
	v_mov_b32_e32 v230, 0
	v_mov_b32_e32 v229, v188
	v_mov_b32_e32 v204, 0
	s_branch .LBB0_553
.LBB0_561:
	v_sub_f32_e32 v227, 0, v246
	v_sub_f32_e32 v221, 0, v250
	s_cmp_lt_i32 s5, 4
	s_cbranch_scc1 .LBB0_567
	v_add_u32_e32 v2, s1, v217
	ds_read_b128 v[84:87], v2
	v_add_u32_e32 v137, s1, v215
	ds_read_b128 v[92:95], v137
	v_add_u32_e32 v136, s1, v218
	ds_read_b128 v[88:91], v136
	v_add_u32_e32 v140, s1, v216
	ds_read_b128 v[96:99], v140
	ds_read_b128 v[100:103], v2 offset:4096
	ds_read_b128 v[104:107], v136 offset:4096
	ds_read_b128 v[108:111], v137 offset:4096
	ds_read_b128 v[112:115], v140 offset:4096
	ds_read_b128 v[116:119], v2 offset:8192
	ds_read_b128 v[120:123], v136 offset:8192
	ds_read_b128 v[124:127], v137 offset:8192
	ds_read_b128 v[128:131], v140 offset:8192
	ds_read_b128 v[132:135], v2 offset:12288
	ds_read_b128 v[148:151], v136 offset:12288
	ds_read_b128 v[136:139], v137 offset:12288
	ds_read_b128 v[152:155], v140 offset:12288
	s_waitcnt lgkmcnt(11)
	v_mfma_f32_16x16x32_bf16 v[100:103], v[100:103], v[80:83], 0
	v_add_u32_e32 v2, s1, v214
	s_lshl_b32 s0, s6, 1
	s_sub_i32 s0, s0, s4
	v_mfma_f32_16x16x32_bf16 v[84:87], v[84:87], v[80:83], 0
	s_lshl_b32 s0, s0, 6
	s_add_i32 s0, s0, 64
	s_waitcnt lgkmcnt(7)
	v_mfma_f32_16x16x32_bf16 v[116:119], v[116:119], v[80:83], 0
	s_waitcnt lgkmcnt(3)
	v_mfma_f32_16x16x32_bf16 v[80:83], v[132:135], v[80:83], 0
	v_mfma_f32_16x16x32_bf16 v[92:95], v[92:95], v[76:79], 0
	v_mfma_f32_16x16x32_bf16 v[108:111], v[108:111], v[76:79], 0
	v_mfma_f32_16x16x32_bf16 v[124:127], v[124:127], v[76:79], 0
	s_waitcnt lgkmcnt(1)
	v_mfma_f32_16x16x32_bf16 v[76:79], v[136:139], v[76:79], 0
	v_mfma_f32_16x16x32_bf16 v[158:161], v[88:91], v[68:71], v[84:87]
	v_mfma_f32_16x16x32_bf16 v[162:165], v[104:107], v[68:71], v[100:103]
	v_mfma_f32_16x16x32_bf16 v[166:169], v[120:123], v[68:71], v[116:119]
	v_mfma_f32_16x16x32_bf16 v[170:173], v[148:151], v[68:71], v[80:83]
	s_nop 1
	ds_read_b64_tr_b16 v[116:117], v2 offset:16384
	ds_read_b64_tr_b16 v[118:119], v2 offset:20480
	ds_read_b64_tr_b16 v[68:69], v2 offset:24576
	ds_read_b64_tr_b16 v[70:71], v2 offset:28672
	v_add_u32_e32 v2, s1, v213
	v_mfma_f32_16x16x32_bf16 v[144:147], v[96:99], v[72:75], v[92:95]
	v_mfma_f32_16x16x32_bf16 v[140:143], v[112:115], v[72:75], v[108:111]
	v_mfma_f32_16x16x32_bf16 v[136:139], v[128:131], v[72:75], v[124:127]
	s_waitcnt lgkmcnt(4)
	v_mfma_f32_16x16x32_bf16 v[132:135], v[152:155], v[72:75], v[76:79]
	ds_read_b64_tr_b16 v[128:129], v2 offset:16384
	ds_read_b64_tr_b16 v[130:131], v2 offset:20480
	ds_read_b64_tr_b16 v[72:73], v2 offset:24576
	ds_read_b64_tr_b16 v[74:75], v2 offset:28672
	v_add_u32_e32 v2, s1, v212
	ds_read_b64_tr_b16 v[124:125], v2 offset:16384
	ds_read_b64_tr_b16 v[126:127], v2 offset:20480
	ds_read_b64_tr_b16 v[76:77], v2 offset:24576
	ds_read_b64_tr_b16 v[78:79], v2 offset:28672
	v_add_u32_e32 v2, s1, v211
	ds_read_b64_tr_b16 v[120:121], v2 offset:16384
	ds_read_b64_tr_b16 v[122:123], v2 offset:20480
	ds_read_b64_tr_b16 v[88:89], v2 offset:24576
	ds_read_b64_tr_b16 v[90:91], v2 offset:28672
	v_add_u32_e32 v2, s1, v208
	ds_read_b64_tr_b16 v[112:113], v2 offset:16384
	ds_read_b64_tr_b16 v[114:115], v2 offset:20480
	ds_read_b64_tr_b16 v[96:97], v2 offset:24576
	ds_read_b64_tr_b16 v[98:99], v2 offset:28672
	v_add_u32_e32 v2, s1, v207
	ds_read_b64_tr_b16 v[108:109], v2 offset:16384
	ds_read_b64_tr_b16 v[110:111], v2 offset:20480
	ds_read_b64_tr_b16 v[92:93], v2 offset:24576
	ds_read_b64_tr_b16 v[94:95], v2 offset:28672
	v_add_u32_e32 v2, s1, v206
	ds_read_b64_tr_b16 v[104:105], v2 offset:16384
	ds_read_b64_tr_b16 v[106:107], v2 offset:20480
	ds_read_b64_tr_b16 v[84:85], v2 offset:24576
	ds_read_b64_tr_b16 v[86:87], v2 offset:28672
	v_add_u32_e32 v2, s1, v205
	v_or_b32_e32 v155, s0, v201
	ds_read_b64_tr_b16 v[100:101], v2 offset:16384
	ds_read_b64_tr_b16 v[102:103], v2 offset:20480
	ds_read_b64_tr_b16 v[80:81], v2 offset:24576
	ds_read_b64_tr_b16 v[82:83], v2 offset:28672
	v_cmp_gt_i32_e64 s[0:1], v155, v200
	v_mov_b32_e32 v2, s46
	v_cmp_lt_i32_e64 s[36:37], v155, v200
	v_cndmask_b32_e64 v2, v158, v2, s[0:1]
	s_nop 0
	v_cndmask_b32_e64 v157, v2, v158, s[36:37]
	v_or_b32_e32 v2, 2, v155
	v_cmp_gt_i32_e64 s[4:5], v2, v200
	v_or_b32_e32 v2, 3, v155
	v_cmp_gt_i32_e64 s[6:7], v2, v200
	v_or_b32_e32 v2, 16, v155
	v_cmp_gt_i32_e64 s[8:9], v2, v200
	v_mov_b32_e32 v2, s46
	v_cndmask_b32_e64 v158, v210, v159, s[36:37]
	v_cndmask_b32_e64 v159, v160, v210, s[4:5]
	v_cndmask_b32_e64 v160, v162, v2, s[8:9]
	v_or_b32_e32 v2, 17, v155
	v_cmp_gt_i32_e64 s[10:11], v2, v200
	v_or_b32_e32 v2, 18, v155
	v_cmp_gt_i32_e64 s[12:13], v2, v200
	v_or_b32_e32 v2, 19, v155
	v_cmp_gt_i32_e64 s[14:15], v2, v200
	v_or_b32_e32 v2, 32, v155
	v_cmp_gt_i32_e64 s[18:19], v2, v200
	v_mov_b32_e32 v2, s46
	v_cndmask_b32_e64 v161, v161, v210, s[6:7]
	v_cndmask_b32_e64 v148, v166, v2, s[18:19]
	v_or_b32_e32 v2, 33, v155
	v_cmp_gt_i32_e64 s[20:21], v2, v200
	v_or_b32_e32 v2, 34, v155
	v_cmp_gt_i32_e64 s[22:23], v2, v200
	v_or_b32_e32 v2, 35, v155
	v_cmp_gt_i32_e64 s[24:25], v2, v200
	v_or_b32_e32 v2, 48, v155
	v_cmp_gt_i32_e64 s[26:27], v2, v200
	v_mov_b32_e32 v2, s46
	v_max_f32_e32 v156, v158, v158
	v_cndmask_b32_e64 v150, v170, v2, s[26:27]
	v_or_b32_e32 v2, 49, v155
	v_cmp_gt_i32_e64 s[28:29], v2, v200
	v_or_b32_e32 v2, 50, v155
	v_cmp_gt_i32_e64 s[30:31], v2, v200
	v_or_b32_e32 v2, 51, v155
	v_cmp_gt_i32_e64 s[34:35], v2, v200
	v_max_f32_e32 v2, v157, v157
	v_cndmask_b32_e64 v162, v163, v210, s[10:11]
	v_cndmask_b32_e64 v163, v164, v210, s[12:13]
	v_cndmask_b32_e64 v164, v165, v210, s[14:15]
	v_max_f32_e32 v2, v2, v156
	v_max_f32_e32 v156, v161, v161
	v_max_f32_e32 v165, v159, v159
	v_max_f32_e32 v156, v165, v156
	v_max_f32_e32 v165, v164, v164
	v_max_f32_e32 v166, v163, v163
	v_max_f32_e32 v165, v166, v165
	v_cndmask_b32_e64 v151, v168, v210, s[22:23]
	v_cndmask_b32_e64 v154, v169, v210, s[24:25]
	v_max3_f32 v165, v160, v162, v165
	v_cndmask_b32_e64 v153, v172, v210, s[30:31]
	v_cndmask_b32_e64 v155, v173, v210, s[34:35]
	v_max3_f32 v2, v2, v156, v165
	v_max_f32_e32 v156, v154, v154
	v_max_f32_e32 v165, v151, v151
	v_max_f32_e32 v156, v165, v156
	v_max_f32_e32 v165, v155, v155
	v_max_f32_e32 v166, v153, v153
	v_cndmask_b32_e64 v149, v167, v210, s[20:21]
	v_cndmask_b32_e64 v152, v171, v210, s[28:29]
	v_max_f32_e32 v165, v166, v165
	v_max3_f32 v156, v148, v149, v156
	v_max3_f32 v165, v150, v152, v165
	v_max3_f32 v2, v2, v156, v165
	v_mov_b32_e32 v156, v2
	s_nop 1
	v_permlane16_swap_b32_e32 v2, v156
	v_max_f32_e32 v156, v156, v156
	v_max_f32_e32 v2, v2, v2
	v_max_f32_e32 v2, v2, v156
	v_mov_b32_e32 v156, v2
	s_nop 1
	v_permlane32_swap_b32_e32 v2, v156
	v_max3_f32 v156, v227, v2, v156
	v_sub_f32_e32 v2, v227, v156
	v_exp_f32_e32 v2, v2
	s_nop 0
	v_cmp_neq_f32_e32 vcc, 1.0, v2
	s_cbranch_vccz .LBB0_564
	v_pk_mul_f32 v[34:35], v[34:35], v[2:3] op_sel_hi:[1,0]
	v_pk_mul_f32 v[30:31], v[30:31], v[2:3] op_sel_hi:[1,0]
	v_pk_mul_f32 v[26:27], v[26:27], v[2:3] op_sel_hi:[1,0]
	v_pk_mul_f32 v[22:23], v[22:23], v[2:3] op_sel_hi:[1,0]
	v_pk_mul_f32 v[18:19], v[18:19], v[2:3] op_sel_hi:[1,0]
	v_pk_mul_f32 v[14:15], v[14:15], v[2:3] op_sel_hi:[1,0]
	v_pk_mul_f32 v[10:11], v[10:11], v[2:3] op_sel_hi:[1,0]
	v_pk_mul_f32 v[6:7], v[6:7], v[2:3] op_sel_hi:[1,0]
	v_pk_mul_f32 v[32:33], v[32:33], v[2:3] op_sel_hi:[1,0]
	v_pk_mul_f32 v[28:29], v[28:29], v[2:3] op_sel_hi:[1,0]
	v_pk_mul_f32 v[24:25], v[24:25], v[2:3] op_sel_hi:[1,0]
	v_pk_mul_f32 v[20:21], v[20:21], v[2:3] op_sel_hi:[1,0]
	v_pk_mul_f32 v[16:17], v[16:17], v[2:3] op_sel_hi:[1,0]
	v_pk_mul_f32 v[12:13], v[12:13], v[2:3] op_sel_hi:[1,0]
	v_pk_mul_f32 v[8:9], v[8:9], v[2:3] op_sel_hi:[1,0]
	v_pk_mul_f32 v[4:5], v[4:5], v[2:3] op_sel_hi:[1,0]

.LBB0_567:
	v_mov_b32_e32 v68, v189
	s_nop 1
	v_permlane16_swap_b32_e32 v189, v68
	v_add_f32_e32 v68, v189, v68
	v_mov_b32_e32 v69, v68
	s_nop 1
	v_permlane32_swap_b32_e32 v68, v69
	v_add_f32_e32 v68, v68, v69
	v_mov_b32_e32 v69, v188
	s_nop 1
	v_permlane16_swap_b32_e32 v188, v69
	v_add_f32_e32 v69, v188, v69
	v_mov_b32_e32 v70, v69
	s_nop 1
	v_permlane32_swap_b32_e32 v69, v70
	v_add_f32_e32 v69, v69, v70
	v_div_scale_f32 v70, s[0:1], v68, v68, 1.0
	v_rcp_f32_e32 v71, v70
	v_readlane_b32 s4, v254, 13
	v_lshlrev_b32_e32 v2, 2, v201
	v_readlane_b32 s10, v254, 19
	v_fma_f32 v72, -v70, v71, 1.0
	v_fmac_f32_e32 v71, v72, v71
	v_div_scale_f32 v72, vcc, 1.0, v68, 1.0
	v_mul_f32_e32 v73, v72, v71
	v_fma_f32 v74, -v70, v73, v72
	v_fmac_f32_e32 v73, v74, v71
	v_fma_f32 v70, -v70, v73, v72
	v_div_fmas_f32 v70, v70, v71, v73
	v_div_fixup_f32 v100, v70, v68, 1.0
	v_div_scale_f32 v68, s[0:1], v69, v69, v196
	v_rcp_f32_e32 v70, v68
	v_readlane_b32 s11, v254, 20
	s_barrier
	v_fma_f32 v71, -v68, v70, 1.0
	v_fmac_f32_e32 v70, v71, v70
	v_div_scale_f32 v71, vcc, v196, v69, v196
	v_mul_f32_e32 v72, v71, v70
	v_fma_f32 v73, -v68, v72, v71
	v_fmac_f32_e32 v72, v73, v70
	v_fma_f32 v68, -v68, v72, v71
	v_div_fmas_f32 v68, v68, v70, v72
	v_div_fixup_f32 v102, v68, v69, v196
	global_load_dwordx4 v[68:71], v2, s[10:11] offset:448
	global_load_dwordx4 v[72:75], v2, s[10:11] offset:384
	global_load_dwordx4 v[76:79], v2, s[10:11] offset:320
	global_load_dwordx4 v[80:83], v2, s[10:11] offset:256
	global_load_dwordx4 v[84:87], v2, s[10:11] offset:192
	global_load_dwordx4 v[88:91], v2, s[10:11] offset:128
	global_load_dwordx4 v[92:95], v2, s[10:11] offset:64
	global_load_dwordx4 v[96:99], v2, s[10:11]
	v_pk_mul_f32 v[66:67], v[66:67], v[102:103] op_sel_hi:[1,0]
	v_pk_mul_f32 v[64:65], v[64:65], v[102:103] op_sel_hi:[1,0]
	v_pk_fma_f32 v[6:7], v[6:7], v[100:101], v[66:67] op_sel_hi:[1,0,1] neg_lo:[0,0,1] neg_hi:[0,0,1]
	v_pk_fma_f32 v[66:67], v[4:5], v[100:101], v[64:65] op_sel_hi:[1,0,1] neg_lo:[0,0,1] neg_hi:[0,0,1]
	v_lshlrev_b64 v[104:105], 11, v[198:199]
	v_mul_f32_e32 v2, v67, v67
	v_pk_fma_f32 v[4:5], v[66:67], v[66:67], v[2:3] op_sel_hi:[1,1,0]
	v_lshl_add_u64 v[104:105], s[86:87], 0, v[104:105]
	s_lshl_b32 s54, s54, 1
	s_mov_b32 s55, s95
	v_pk_fma_f32 v[4:5], v[6:7], v[6:7], v[4:5]
	v_mul_f32_e32 v2, v7, v7
	v_pk_mul_f32 v[60:61], v[60:61], v[102:103] op_sel_hi:[1,0]
	v_lshl_add_u64 v[104:105], v[104:105], 0, s[54:55]
	v_pk_add_f32 v[106:107], v[2:3], v[4:5] op_sel_hi:[0,1]
	v_lshlrev_b32_e32 v2, 1, v201
	v_pk_fma_f32 v[8:9], v[8:9], v[100:101], v[60:61] op_sel_hi:[1,0,1] neg_lo:[0,0,1] neg_hi:[0,0,1]
	v_lshl_add_u64 v[64:65], v[104:105], 0, v[2:3]
	v_pk_mul_f32 v[62:63], v[62:63], v[102:103] op_sel_hi:[1,0]
	v_pk_fma_f32 v[60:61], v[8:9], v[8:9], v[106:107]
	v_mul_f32_e32 v2, v9, v9
	v_pk_fma_f32 v[10:11], v[10:11], v[100:101], v[62:63] op_sel_hi:[1,0,1] neg_lo:[0,0,1] neg_hi:[0,0,1]
	v_pk_add_f32 v[60:61], v[2:3], v[60:61] op_sel_hi:[0,1]
	v_pk_fma_f32 v[60:61], v[10:11], v[10:11], v[60:61]
	v_mul_f32_e32 v2, v11, v11
	v_pk_mul_f32 v[56:57], v[56:57], v[102:103] op_sel_hi:[1,0]
	v_pk_add_f32 v[60:61], v[2:3], v[60:61] op_sel_hi:[0,1]
	v_pk_fma_f32 v[12:13], v[12:13], v[100:101], v[56:57] op_sel_hi:[1,0,1] neg_lo:[0,0,1] neg_hi:[0,0,1]
	v_pk_mul_f32 v[58:59], v[58:59], v[102:103] op_sel_hi:[1,0]
	v_pk_fma_f32 v[56:57], v[12:13], v[12:13], v[60:61]
	v_mul_f32_e32 v2, v13, v13
	v_pk_fma_f32 v[14:15], v[14:15], v[100:101], v[58:59] op_sel_hi:[1,0,1] neg_lo:[0,0,1] neg_hi:[0,0,1]
	v_pk_add_f32 v[56:57], v[2:3], v[56:57] op_sel_hi:[0,1]
	v_pk_fma_f32 v[56:57], v[14:15], v[14:15], v[56:57]
	v_mul_f32_e32 v2, v15, v15
	v_pk_mul_f32 v[52:53], v[52:53], v[102:103] op_sel_hi:[1,0]
	v_pk_add_f32 v[56:57], v[2:3], v[56:57] op_sel_hi:[0,1]
	v_pk_fma_f32 v[16:17], v[16:17], v[100:101], v[52:53] op_sel_hi:[1,0,1] neg_lo:[0,0,1] neg_hi:[0,0,1]
	v_pk_mul_f32 v[54:55], v[54:55], v[102:103] op_sel_hi:[1,0]
	v_pk_fma_f32 v[52:53], v[16:17], v[16:17], v[56:57]
	v_mul_f32_e32 v2, v17, v17
	v_pk_fma_f32 v[18:19], v[18:19], v[100:101], v[54:55] op_sel_hi:[1,0,1] neg_lo:[0,0,1] neg_hi:[0,0,1]
	v_pk_add_f32 v[52:53], v[2:3], v[52:53] op_sel_hi:[0,1]
	v_pk_fma_f32 v[52:53], v[18:19], v[18:19], v[52:53]
	v_mul_f32_e32 v2, v19, v19
	v_pk_mul_f32 v[48:49], v[48:49], v[102:103] op_sel_hi:[1,0]
	v_pk_add_f32 v[52:53], v[2:3], v[52:53] op_sel_hi:[0,1]
	v_pk_fma_f32 v[20:21], v[20:21], v[100:101], v[48:49] op_sel_hi:[1,0,1] neg_lo:[0,0,1] neg_hi:[0,0,1]
	v_pk_mul_f32 v[50:51], v[50:51], v[102:103] op_sel_hi:[1,0]
	v_pk_fma_f32 v[48:49], v[20:21], v[20:21], v[52:53]
	v_mul_f32_e32 v2, v21, v21
	v_pk_fma_f32 v[22:23], v[22:23], v[100:101], v[50:51] op_sel_hi:[1,0,1] neg_lo:[0,0,1] neg_hi:[0,0,1]
	v_pk_add_f32 v[48:49], v[2:3], v[48:49] op_sel_hi:[0,1]
	v_pk_fma_f32 v[48:49], v[22:23], v[22:23], v[48:49]
	v_mul_f32_e32 v2, v23, v23
	v_pk_mul_f32 v[44:45], v[44:45], v[102:103] op_sel_hi:[1,0]
	v_pk_add_f32 v[48:49], v[2:3], v[48:49] op_sel_hi:[0,1]
	v_pk_fma_f32 v[24:25], v[24:25], v[100:101], v[44:45] op_sel_hi:[1,0,1] neg_lo:[0,0,1] neg_hi:[0,0,1]
	v_pk_mul_f32 v[46:47], v[46:47], v[102:103] op_sel_hi:[1,0]
	v_pk_fma_f32 v[44:45], v[24:25], v[24:25], v[48:49]
	v_mul_f32_e32 v2, v25, v25
	v_pk_fma_f32 v[26:27], v[26:27], v[100:101], v[46:47] op_sel_hi:[1,0,1] neg_lo:[0,0,1] neg_hi:[0,0,1]
	v_pk_add_f32 v[44:45], v[2:3], v[44:45] op_sel_hi:[0,1]
	v_pk_fma_f32 v[44:45], v[26:27], v[26:27], v[44:45]
	v_mul_f32_e32 v2, v27, v27
	v_pk_mul_f32 v[40:41], v[40:41], v[102:103] op_sel_hi:[1,0]
	v_pk_add_f32 v[44:45], v[2:3], v[44:45] op_sel_hi:[0,1]
	v_pk_fma_f32 v[28:29], v[28:29], v[100:101], v[40:41] op_sel_hi:[1,0,1] neg_lo:[0,0,1] neg_hi:[0,0,1]
	v_pk_mul_f32 v[42:43], v[42:43], v[102:103] op_sel_hi:[1,0]
	v_pk_fma_f32 v[40:41], v[28:29], v[28:29], v[44:45]
	v_mul_f32_e32 v2, v29, v29
	v_pk_fma_f32 v[30:31], v[30:31], v[100:101], v[42:43] op_sel_hi:[1,0,1] neg_lo:[0,0,1] neg_hi:[0,0,1]
	v_pk_add_f32 v[40:41], v[2:3], v[40:41] op_sel_hi:[0,1]
	v_pk_fma_f32 v[40:41], v[30:31], v[30:31], v[40:41]
	v_mul_f32_e32 v2, v31, v31
	v_pk_mul_f32 v[36:37], v[36:37], v[102:103] op_sel_hi:[1,0]
	v_pk_add_f32 v[40:41], v[2:3], v[40:41] op_sel_hi:[0,1]
	v_pk_fma_f32 v[32:33], v[32:33], v[100:101], v[36:37] op_sel_hi:[1,0,1] neg_lo:[0,0,1] neg_hi:[0,0,1]
	v_pk_mul_f32 v[38:39], v[38:39], v[102:103] op_sel_hi:[1,0]
	v_pk_fma_f32 v[36:37], v[32:33], v[32:33], v[40:41]
	v_mul_f32_e32 v2, v33, v33
	v_pk_fma_f32 v[34:35], v[34:35], v[100:101], v[38:39] op_sel_hi:[1,0,1] neg_lo:[0,0,1] neg_hi:[0,0,1]
	v_pk_add_f32 v[36:37], v[2:3], v[36:37] op_sel_hi:[0,1]
	v_pk_fma_f32 v[36:37], v[34:35], v[34:35], v[36:37]
	v_mul_f32_e32 v2, v35, v35
	v_pk_add_f32 v[36:37], v[2:3], v[36:37] op_sel_hi:[0,1]
	v_mov_b32_e32 v2, v36
	s_nop 1
	v_permlane16_swap_b32_e32 v36, v2
	v_add_f32_e32 v2, v36, v2
	v_mov_b32_e32 v36, v2
	s_nop 1
	v_permlane32_swap_b32_e32 v2, v36
	s_mov_b64 s[0:1], 0x10000400
	v_add_f32_e32 v2, v2, v36
	v_lshl_add_u64 v[4:5], v[64:65], 0, s[0:1]
	v_fmamk_f32 v2, v2, 0x3c000000, v197
	s_mov_b32 s0, 0xf800000
	v_cmp_gt_f32_e32 vcc, s0, v2
	v_mul_f32_e32 v36, 0x4f800000, v2
	s_waitcnt vmcnt(0)
	v_readlane_b32 s17, v254, 26
	v_cndmask_b32_e32 v2, v2, v36, vcc
	v_sqrt_f32_e32 v36, v2
	s_xor_b32 s57, s57, 31
	s_mov_b32 s4, 0x8000
	v_readlane_b32 s5, v254, 14
	v_add_u32_e32 v37, -1, v36
	v_fma_f32 v38, -v37, v36, v2
	v_cmp_ge_f32_e64 s[0:1], 0, v38
	v_add_u32_e32 v38, 1, v36
	s_lshl_b32 s5, s57, 17
	v_cndmask_b32_e64 v37, v36, v37, s[0:1]
	v_fma_f32 v36, -v38, v36, v2
	v_cmp_lt_f32_e64 s[0:1], 0, v36
	v_mov_b32_e32 v56, v3
	v_mov_b32_e32 v57, v3
	v_cndmask_b32_e64 v36, v37, v38, s[0:1]
	v_mul_f32_e32 v37, 0x37800000, v36
	v_cndmask_b32_e32 v36, v36, v37, vcc
	v_cmp_class_f32_e32 vcc, v2, v209
	v_mov_b32_e32 v58, v3
	v_mov_b32_e32 v59, v3
	v_cndmask_b32_e32 v2, v36, v2, vcc
	v_div_scale_f32 v36, s[0:1], v2, v2, s47
	v_rcp_f32_e32 v37, v36
	s_brev_b32 s0, 8
	s_mov_b32 s1, s89
	v_mov_b64_e32 v[52:53], v[56:57]
	v_fma_f32 v38, -v36, v37, 1.0
	v_fmac_f32_e32 v37, v38, v37
	v_div_scale_f32 v38, vcc, s47, v2, s47
	v_mul_f32_e32 v39, v38, v37
	v_fma_f32 v40, -v36, v39, v38
	v_fmac_f32_e32 v39, v40, v37
	v_fma_f32 v36, -v36, v39, v38
	v_div_fmas_f32 v36, v36, v37, v39
	v_div_fixup_f32 v2, v36, v2, s47
	v_pk_mul_f32 v[36:37], v[66:67], v[2:3] op_sel_hi:[1,0]
	v_pk_mul_f32 v[6:7], v[6:7], v[2:3] op_sel_hi:[1,0]
	v_pk_mul_f32 v[36:37], v[96:97], v[36:37]
	v_pk_mul_f32 v[6:7], v[98:99], v[6:7]
	v_cvt_pk_bf16_f32 v36, v36, v37
	v_cvt_pk_bf16_f32 v37, v6, v7
	v_add_co_u32_e32 v6, vcc, s0, v64
	v_mov_b64_e32 v[62:63], v[58:59]
	s_nop 0
	v_addc_co_u32_e32 v7, vcc, 0, v65, vcc
	global_store_dwordx2 v[6:7], v[36:37], off offset:1024
	v_pk_mul_f32 v[6:7], v[8:9], v[2:3] op_sel_hi:[1,0]
	v_pk_mul_f32 v[8:9], v[10:11], v[2:3] op_sel_hi:[1,0]
	v_pk_mul_f32 v[6:7], v[92:93], v[6:7]
	v_pk_mul_f32 v[8:9], v[94:95], v[8:9]
	v_cvt_pk_bf16_f32 v6, v6, v7
	v_cvt_pk_bf16_f32 v7, v8, v9
	global_store_dwordx2 v[4:5], v[6:7], off offset:32
	v_pk_mul_f32 v[6:7], v[12:13], v[2:3] op_sel_hi:[1,0]
	v_pk_mul_f32 v[8:9], v[14:15], v[2:3] op_sel_hi:[1,0]
	v_pk_mul_f32 v[6:7], v[88:89], v[6:7]
	v_pk_mul_f32 v[8:9], v[90:91], v[8:9]
	v_cvt_pk_bf16_f32 v6, v6, v7
	v_cvt_pk_bf16_f32 v7, v8, v9
	global_store_dwordx2 v[4:5], v[6:7], off offset:64
	v_pk_mul_f32 v[6:7], v[16:17], v[2:3] op_sel_hi:[1,0]
	v_pk_mul_f32 v[8:9], v[18:19], v[2:3] op_sel_hi:[1,0]
	v_pk_mul_f32 v[6:7], v[84:85], v[6:7]
	v_pk_mul_f32 v[8:9], v[86:87], v[8:9]
	v_cvt_pk_bf16_f32 v6, v6, v7
	v_cvt_pk_bf16_f32 v7, v8, v9
	global_store_dwordx2 v[4:5], v[6:7], off offset:96
	v_pk_mul_f32 v[6:7], v[20:21], v[2:3] op_sel_hi:[1,0]
	v_pk_mul_f32 v[8:9], v[22:23], v[2:3] op_sel_hi:[1,0]
	v_pk_mul_f32 v[6:7], v[80:81], v[6:7]
	v_pk_mul_f32 v[8:9], v[82:83], v[8:9]
	v_cvt_pk_bf16_f32 v6, v6, v7
	v_cvt_pk_bf16_f32 v7, v8, v9
	global_store_dwordx2 v[4:5], v[6:7], off offset:128
	v_pk_mul_f32 v[6:7], v[24:25], v[2:3] op_sel_hi:[1,0]
	v_pk_mul_f32 v[8:9], v[26:27], v[2:3] op_sel_hi:[1,0]
	v_pk_mul_f32 v[6:7], v[76:77], v[6:7]
	v_pk_mul_f32 v[8:9], v[78:79], v[8:9]
	v_cvt_pk_bf16_f32 v6, v6, v7
	v_cvt_pk_bf16_f32 v7, v8, v9
	global_store_dwordx2 v[4:5], v[6:7], off offset:160
	v_pk_mul_f32 v[6:7], v[28:29], v[2:3] op_sel_hi:[1,0]
	v_pk_mul_f32 v[8:9], v[30:31], v[2:3] op_sel_hi:[1,0]
	v_pk_mul_f32 v[6:7], v[72:73], v[6:7]
	v_pk_mul_f32 v[8:9], v[74:75], v[8:9]
	v_cvt_pk_bf16_f32 v6, v6, v7
	v_cvt_pk_bf16_f32 v7, v8, v9
	global_store_dwordx2 v[4:5], v[6:7], off offset:192
	v_pk_mul_f32 v[6:7], v[32:33], v[2:3] op_sel_hi:[1,0]
	v_pk_mul_f32 v[8:9], v[34:35], v[2:3] op_sel_hi:[1,0]
	v_pk_mul_f32 v[6:7], v[68:69], v[6:7]
	v_pk_mul_f32 v[8:9], v[70:71], v[8:9]
	v_cvt_pk_bf16_f32 v6, v6, v7
	v_cvt_pk_bf16_f32 v7, v8, v9
	v_mov_b32_e32 v10, v0
	global_store_dwordx2 v[4:5], v[6:7], off offset:224
	v_mov_b32_e32 v23, v3
	v_readfirstlane_b32 s0, v10
	s_ashr_i32 s17, s0, 6
	v_and_b32_e32 v13, 15, v10
	v_lshl_or_b32 v200, s17, 4, v13
	s_lshl_b32 s0, s57, 7
	s_or_b32 s0, s88, s0
	v_ashrrev_i32_e32 v201, 31, v200
	v_lshl_add_u64 v[198:199], s[0:1], 0, v[200:201]
	v_lshlrev_b64 v[4:5], 10, v[198:199]
	v_bfe_u32 v12, v10, 4, 2
	v_lshl_add_u64 v[4:5], s[64:65], 0, v[4:5]
	v_lshl_add_u64 v[4:5], v[4:5], 0, s[54:55]
	v_lshlrev_b32_e32 v2, 4, v12
	v_lshl_add_u64 v[4:5], v[4:5], 0, v[2:3]
	global_load_dwordx4 v[48:51], v[4:5], off
	global_load_dwordx4 v[36:39], v[4:5], off offset:64
	global_load_dwordx4 v[44:47], v[4:5], off offset:128
	global_load_dwordx4 v[40:43], v[4:5], off offset:192
	v_ashrrev_i32_e32 v4, 4, v10
	v_ashrrev_i32_e32 v5, 31, v4
	v_lshrrev_b32_e32 v11, 4, v10
	v_lshl_add_u64 v[6:7], s[88:89], 0, v[4:5]
	v_lshlrev_b64 v[6:7], 10, v[6:7]
	v_lshlrev_b32_e32 v15, 8, v13
	v_bitop3_b32 v11, v11, v13, 3 bitop3:0x6c
	v_lshl_add_u64 v[8:9], s[68:69], 0, v[6:7]
	v_lshl_or_b32 v221, v11, 4, v15
	v_bitop3_b32 v11, v12, v13, 4 bitop3:0x36
	v_lshl_add_u64 v[8:9], v[8:9], 0, s[54:55]
	v_lshlrev_b32_e32 v2, 4, v13
	v_lshl_or_b32 v227, v11, 4, v15
	v_bitop3_b32 v11, v12, v13, 8 bitop3:0x36
	v_lshl_add_u64 v[202:203], v[8:9], 0, v[2:3]
	v_xor_b32_e32 v8, v4, v10
	v_lshl_or_b32 v219, v11, 4, v15
	v_bitop3_b32 v11, v12, v13, 12 bitop3:0x36
	v_lshlrev_b32_e32 v8, 4, v8
	v_lshl_or_b32 v220, v11, 4, v15
	v_lshlrev_b32_e32 v11, 8, v4
	v_bfe_u32 v9, v10, 1, 3
	v_lshlrev_b32_e32 v14, 4, v10
	v_and_or_b32 v228, v8, s2, v11
	v_bfe_u32 v8, v10, 2, 2
	v_lshlrev_b32_e32 v201, 2, v12
	v_lshlrev_b32_e32 v10, 3, v10
	v_or_b32_e32 v8, v201, v8
	v_and_b32_e32 v10, 24, v10
	v_lshl_or_b32 v10, v8, 8, v10
	v_lshlrev_b32_e32 v8, 5, v8
	v_lshl_add_u64 v[6:7], s[66:67], 0, v[6:7]
	v_and_b32_e32 v12, 0xe0, v8
	s_movk_i32 s0, 0x80
	v_lshl_add_u64 v[6:7], v[6:7], 0, s[54:55]
	v_bitop3_b32 v214, v12, s0, v10 bitop3:0x36
	s_movk_i32 s0, 0xa0
	v_bitop3_b32 v9, v9, v4, 7 bitop3:0x78
	v_bitop3_b32 v213, v12, s0, v10 bitop3:0x36
	s_movk_i32 s0, 0xc0
	v_lshl_add_u64 v[204:205], v[6:7], 0, v[2:3]
	v_lshlrev_b32_e32 v9, 5, v9
	v_and_b32_e32 v14, 16, v14
	v_or_b32_e32 v218, v12, v10
	v_bitop3_b32 v217, v12, 32, v10 bitop3:0x36
	v_bitop3_b32 v216, v12, 64, v10 bitop3:0x36
	v_bitop3_b32 v215, v12, s71, v10 bitop3:0x36
	v_bitop3_b32 v212, v12, s0, v10 bitop3:0x36
	v_bitop3_b32 v211, v8, s59, v10 bitop3:0x26
	v_add_co_u32_e32 v10, vcc, s4, v204
	v_or3_b32 v229, v9, v14, v11
	s_nop 0
	v_addc_co_u32_e32 v11, vcc, 0, v205, vcc
	global_load_dwordx4 v[6:9], v[204:205], off
	v_add_co_u32_e32 v18, vcc, s4, v202
	global_load_dwordx4 v[10:13], v[10:11], off
	s_nop 0
	global_load_dwordx4 v[14:17], v[202:203], off
	v_addc_co_u32_e32 v19, vcc, 0, v203, vcc
	global_load_dwordx4 v[18:21], v[18:19], off
	s_add_u32 s0, s58, s82
	v_lshlrev_b64 v[4:5], 10, v[4:5]
	s_addc_u32 s1, 0, s83
	v_add_u32_e32 v22, 0, v228
	v_lshl_add_u64 v[4:5], s[0:1], 0, v[4:5]
	s_waitcnt vmcnt(3)
	ds_write_b128 v22, v[6:9]
	s_waitcnt vmcnt(2)
	ds_write_b128 v22, v[10:13] offset:8192
	v_add_u32_e32 v6, 0, v229
	v_lshl_add_u64 v[4:5], v[4:5], 0, v[2:3]
	s_waitcnt vmcnt(1)
	ds_write_b128 v6, v[14:17] offset:16384
	s_waitcnt vmcnt(0)
	ds_write_b128 v6, v[18:21] offset:24576
	v_lshl_add_u64 v[206:207], s[86:87], 0, v[4:5]
	v_mov_b32_e32 v4, v3
	v_mov_b32_e32 v5, v3
	v_mov_b32_e32 v6, v3
	v_mov_b32_e32 v7, v3
	v_mov_b32_e32 v8, v3
	v_mov_b32_e32 v9, v3
	v_mov_b32_e32 v10, v3
	v_mov_b32_e32 v11, v3
	v_mov_b32_e32 v12, v3
	v_mov_b32_e32 v13, v3
	v_mov_b32_e32 v14, v3
	v_mov_b32_e32 v15, v3
	v_mov_b32_e32 v16, v3
	v_mov_b32_e32 v17, v3
	v_mov_b32_e32 v18, v3
	v_mov_b32_e32 v19, v3
	v_mov_b32_e32 v20, v3
	v_mov_b32_e32 v21, v3
	v_mov_b32_e32 v22, v3
	v_mov_b32_e32 v24, v3
	v_mov_b32_e32 v25, v3
	v_mov_b32_e32 v26, v3
	v_mov_b32_e32 v27, v3
	v_mov_b32_e32 v28, v3
	v_mov_b32_e32 v29, v3
	v_mov_b32_e32 v30, v3
	v_mov_b32_e32 v31, v3
	v_mov_b32_e32 v32, v3
	v_mov_b32_e32 v33, v3
	v_mov_b32_e32 v2, v3
	v_mov_b64_e32 v[66:67], v[58:59]
	v_mov_b64_e32 v[70:71], v[58:59]
	v_mov_b64_e32 v[74:75], v[58:59]
	v_mov_b64_e32 v[78:79], v[58:59]
	v_mov_b64_e32 v[82:83], v[58:59]
	v_mov_b64_e32 v[34:35], v[32:33]
	v_mov_b32_e32 v231, 0xf149f2ca
	v_mov_b32_e32 v232, 0
	s_mov_b64 s[0:1], 0
	v_mov_b64_e32 v[54:55], v[58:59]
	v_mov_b64_e32 v[60:61], v[56:57]
	v_mov_b64_e32 v[64:65], v[56:57]
	v_mov_b64_e32 v[68:69], v[56:57]
	v_mov_b64_e32 v[72:73], v[56:57]
	v_mov_b64_e32 v[76:77], v[56:57]
	v_mov_b64_e32 v[80:81], v[56:57]
	v_mov_b64_e32 v[32:33], v[30:31]
	v_mov_b64_e32 v[30:31], v[28:29]
	v_mov_b64_e32 v[28:29], v[26:27]
	v_mov_b64_e32 v[26:27], v[24:25]
	v_mov_b64_e32 v[24:25], v[22:23]
	v_mov_b64_e32 v[22:23], v[20:21]
	v_mov_b64_e32 v[20:21], v[18:19]
	v_mov_b64_e32 v[18:19], v[16:17]
	v_mov_b64_e32 v[16:17], v[14:15]
	v_mov_b64_e32 v[14:15], v[12:13]
	v_mov_b64_e32 v[12:13], v[10:11]
	v_mov_b64_e32 v[10:11], v[8:9]
	v_mov_b64_e32 v[8:9], v[6:7]
	v_mov_b64_e32 v[6:7], v[4:5]
	v_mov_b64_e32 v[4:5], v[2:3]
	v_mov_b32_e32 v233, 0
	v_mov_b32_e32 v208, 0xf149f2ca
	v_readlane_b32 s6, v254, 15
	v_readlane_b32 s7, v254, 16
	v_readlane_b32 s8, v254, 17
	v_readlane_b32 s9, v254, 18
	v_readlane_b32 s12, v254, 21
	v_readlane_b32 s13, v254, 22
	v_readlane_b32 s14, v254, 23
	v_readlane_b32 s15, v254, 24
	v_readlane_b32 s16, v254, 25
	v_readlane_b32 s18, v254, 27
	v_readlane_b32 s19, v254, 28
	s_waitcnt lgkmcnt(0)
	s_barrier
	v_mov_b32_e32 v246, 0
	v_mov_b32_e32 v247, 0
	v_mov_b32_e32 v248, 0
	v_mov_b32_e32 v249, 0
	v_mov_b32_e32 v250, 0
	v_mov_b32_e32 v251, 0
.LBB0_568:
	v_lshl_add_u64 v[96:97], v[206:207], 0, s[0:1]
	s_mov_b32 s7, 0xdd10000
	v_add_co_u32_e32 v84, vcc, s7, v96
	s_mov_b32 s7, 0xdd18000
	s_nop 0
	v_addc_co_u32_e32 v85, vcc, 0, v97, vcc
	v_add_co_u32_e32 v88, vcc, s7, v96
	s_mov_b32 s7, 0xee10000
	s_nop 0
	v_addc_co_u32_e32 v89, vcc, 0, v97, vcc
	v_add_co_u32_e32 v92, vcc, s7, v96
	s_mov_b32 s7, 0xee18000
	s_nop 0
	v_addc_co_u32_e32 v93, vcc, 0, v97, vcc
	v_add_co_u32_e32 v96, vcc, s7, v96
	global_load_dwordx4 v[84:87], v[84:85], off
	s_nop 0
	v_addc_co_u32_e32 v97, vcc, 0, v97, vcc
	global_load_dwordx4 v[88:91], v[88:89], off
	s_add_i32 s6, s4, 0xffff8000
	global_load_dwordx4 v[92:95], v[92:93], off
	s_and_b32 s6, s6, 0x8000
	global_load_dwordx4 v[96:99], v[96:97], off
	s_add_i32 s6, s6, 0
	v_add_u32_e32 v148, s6, v221
	ds_read_b128 v[100:103], v148
	v_add_u32_e32 v152, s6, v227
	ds_read_b128 v[104:107], v152
	v_add_u32_e32 v156, s6, v219
	v_add_u32_e32 v160, s6, v220
	s_waitcnt lgkmcnt(1)
	v_mfma_f32_16x16x32_bf16 v[100:103], v[100:103], v[48:51], v[246:249]
	ds_read_b128 v[108:111], v156
	ds_read_b128 v[112:115], v160
	ds_read_b128 v[116:119], v148 offset:4096
	ds_read_b128 v[120:123], v152 offset:4096
	ds_read_b128 v[124:127], v156 offset:4096
	ds_read_b128 v[128:131], v160 offset:4096
	ds_read_b128 v[132:135], v148 offset:8192
	ds_read_b128 v[136:139], v152 offset:8192
	ds_read_b128 v[140:143], v156 offset:8192
	ds_read_b128 v[144:147], v160 offset:8192
	ds_read_b128 v[148:151], v148 offset:12288
	ds_read_b128 v[152:155], v152 offset:12288
	ds_read_b128 v[156:159], v156 offset:12288
	ds_read_b128 v[160:163], v160 offset:12288
	v_mov_b32_e32 v2, v231
	s_waitcnt lgkmcnt(11)
	v_mfma_f32_16x16x32_bf16 v[116:119], v[116:119], v[48:51], v[246:249]
	v_mfma_f32_16x16x32_bf16 v[164:167], v[104:107], v[36:39], v[100:103]
	s_waitcnt lgkmcnt(7)
	v_mfma_f32_16x16x32_bf16 v[132:135], v[132:135], v[48:51], v[246:249]
	s_nop 0
	v_add_u32_e32 v100, s6, v218
	s_nop 3
	v_max_f32_e32 v230, v165, v165
	v_max_f32_e32 v231, v164, v164
	s_waitcnt lgkmcnt(3)
	v_mfma_f32_16x16x32_bf16 v[148:151], v[148:151], v[48:51], v[246:249]
	v_max_f32_e32 v230, v231, v230
	v_max_f32_e32 v231, v167, v167
	v_max_f32_e32 v234, v166, v166
	v_mfma_f32_16x16x32_bf16 v[168:171], v[120:123], v[36:39], v[116:119]
	v_max_f32_e32 v231, v234, v231
	v_add_u32_e32 v102, s6, v211
	v_mov_b32_e32 v246, v251
	v_mov_b32_e32 v247, v251
	v_mov_b32_e32 v248, v251
	v_mov_b32_e32 v249, v251
	v_mfma_f32_16x16x32_bf16 v[188:191], v[136:139], v[36:39], v[132:135]
	s_waitcnt lgkmcnt(2)
	v_mfma_f32_16x16x32_bf16 v[192:195], v[152:155], v[36:39], v[148:151]
	s_nop 2
	v_max_f32_e32 v234, v171, v171
	v_max_f32_e32 v234, v170, v234
	v_max3_f32 v234, v168, v169, v234
	v_max3_f32 v230, v230, v231, v234
	s_waitcnt lgkmcnt(1)
	v_mfma_f32_16x16x32_bf16 v[156:159], v[156:159], v[44:47], v[246:249]
	v_max_f32_e32 v231, v190, v191
	v_max_f32_e32 v235, v194, v194
	v_max_f32_e32 v234, v235, v195
	v_mfma_f32_16x16x32_bf16 v[124:127], v[124:127], v[44:47], v[246:249]
	v_max3_f32 v231, v188, v189, v231
	v_max3_f32 v234, v192, v193, v234
	v_max3_f32 v230, v230, v231, v234
	v_mfma_f32_16x16x32_bf16 v[108:111], v[108:111], v[44:47], v[246:249]
	v_mov_b32_e32 v231, v230
	s_nop 1
	v_permlane16_swap_b32_e32 v230, v231
	v_mfma_f32_16x16x32_bf16 v[140:143], v[140:143], v[44:47], v[246:249]
	v_max_f32_e32 v230, v230, v231
	s_waitcnt lgkmcnt(0)
	v_mfma_f32_16x16x32_bf16 v[184:187], v[160:163], v[40:43], v[156:159]
	ds_read_b64_tr_b16 v[160:161], v100 offset:16384
	ds_read_b64_tr_b16 v[162:163], v100 offset:20480
	ds_read_b64_tr_b16 v[116:117], v100 offset:24576
	ds_read_b64_tr_b16 v[118:119], v100 offset:28672
	v_add_u32_e32 v100, s6, v217
	ds_read_b64_tr_b16 v[156:157], v100 offset:16384
	ds_read_b64_tr_b16 v[158:159], v100 offset:20480
	ds_read_b64_tr_b16 v[120:121], v100 offset:24576
	ds_read_b64_tr_b16 v[122:123], v100 offset:28672
	v_add_u32_e32 v100, s6, v216
	v_mfma_f32_16x16x32_bf16 v[176:179], v[128:131], v[40:43], v[124:127]
	ds_read_b64_tr_b16 v[152:153], v100 offset:16384
	ds_read_b64_tr_b16 v[154:155], v100 offset:20480
	s_nop 0
	ds_read_b64_tr_b16 v[124:125], v100 offset:24576
	ds_read_b64_tr_b16 v[126:127], v100 offset:28672
	v_add_u32_e32 v100, s6, v215
	ds_read_b64_tr_b16 v[148:149], v100 offset:16384
	ds_read_b64_tr_b16 v[150:151], v100 offset:20480
	ds_read_b64_tr_b16 v[128:129], v100 offset:24576
	ds_read_b64_tr_b16 v[130:131], v100 offset:28672
	v_add_u32_e32 v100, s6, v214
	v_mfma_f32_16x16x32_bf16 v[172:175], v[112:115], v[40:43], v[108:111]
	v_mov_b32_e32 v231, v230
	s_nop 1
	v_permlane32_swap_b32_e32 v230, v231
	v_mfma_f32_16x16x32_bf16 v[180:183], v[144:147], v[40:43], v[140:143]
	ds_read_b64_tr_b16 v[144:145], v100 offset:16384
	ds_read_b64_tr_b16 v[146:147], v100 offset:20480
	ds_read_b64_tr_b16 v[112:113], v100 offset:24576
	ds_read_b64_tr_b16 v[114:115], v100 offset:28672
	v_add_u32_e32 v100, s6, v213
	ds_read_b64_tr_b16 v[140:141], v100 offset:16384
	ds_read_b64_tr_b16 v[142:143], v100 offset:20480
	ds_read_b64_tr_b16 v[108:109], v100 offset:24576
	ds_read_b64_tr_b16 v[110:111], v100 offset:28672
	v_add_u32_e32 v100, s6, v212
	ds_read_b64_tr_b16 v[136:137], v100 offset:16384
	ds_read_b64_tr_b16 v[138:139], v100 offset:20480
	ds_read_b64_tr_b16 v[104:105], v100 offset:24576
	ds_read_b64_tr_b16 v[106:107], v100 offset:28672
	ds_read_b64_tr_b16 v[132:133], v102 offset:16384
	ds_read_b64_tr_b16 v[134:135], v102 offset:20480
	ds_read_b64_tr_b16 v[100:101], v102 offset:24576
	ds_read_b64_tr_b16 v[102:103], v102 offset:28672
	v_max3_f32 v231, v2, v230, v231
	v_exp_f32_e64 v2, -v231
	s_nop 0
	v_cmp_neq_f32_e32 vcc, 1.0, v2
	s_cbranch_vccz .LBB0_570
	v_pk_mul_f32 v[34:35], v[34:35], v[2:3] op_sel_hi:[1,0]
	v_pk_mul_f32 v[32:33], v[32:33], v[2:3] op_sel_hi:[1,0]
	v_pk_mul_f32 v[30:31], v[30:31], v[2:3] op_sel_hi:[1,0]
	v_pk_mul_f32 v[28:29], v[28:29], v[2:3] op_sel_hi:[1,0]
	v_pk_mul_f32 v[26:27], v[26:27], v[2:3] op_sel_hi:[1,0]
	v_pk_mul_f32 v[24:25], v[24:25], v[2:3] op_sel_hi:[1,0]
	v_pk_mul_f32 v[22:23], v[22:23], v[2:3] op_sel_hi:[1,0]
	v_pk_mul_f32 v[20:21], v[20:21], v[2:3] op_sel_hi:[1,0]
	v_pk_mul_f32 v[18:19], v[18:19], v[2:3] op_sel_hi:[1,0]
	v_pk_mul_f32 v[16:17], v[16:17], v[2:3] op_sel_hi:[1,0]
	v_pk_mul_f32 v[14:15], v[14:15], v[2:3] op_sel_hi:[1,0]
	v_pk_mul_f32 v[12:13], v[12:13], v[2:3] op_sel_hi:[1,0]
	v_pk_mul_f32 v[10:11], v[10:11], v[2:3] op_sel_hi:[1,0]
	v_pk_mul_f32 v[8:9], v[8:9], v[2:3] op_sel_hi:[1,0]
	v_pk_mul_f32 v[6:7], v[6:7], v[2:3] op_sel_hi:[1,0]
	v_pk_mul_f32 v[4:5], v[4:5], v[2:3] op_sel_hi:[1,0]
	v_sub_f32_e32 v250, v250, v231
	v_sub_f32_e32 v164, v164, v231
	v_sub_f32_e32 v165, v165, v231
	v_sub_f32_e32 v166, v166, v231
	v_sub_f32_e32 v167, v167, v231
	v_sub_f32_e32 v168, v168, v231
	v_sub_f32_e32 v169, v169, v231
	v_sub_f32_e32 v170, v170, v231
	v_sub_f32_e32 v171, v171, v231
	v_sub_f32_e32 v188, v188, v231
	v_sub_f32_e32 v189, v189, v231
	v_sub_f32_e32 v190, v190, v231
	v_sub_f32_e32 v191, v191, v231
	v_sub_f32_e32 v192, v192, v231
	v_sub_f32_e32 v193, v193, v231
	v_sub_f32_e32 v194, v194, v231
	v_sub_f32_e32 v195, v195, v231
.LBB0_570:
	v_max_f32_e32 v230, v172, v173
	v_max_f32_e32 v234, v174, v175
	v_max_f32_e32 v235, v178, v179
	v_max3_f32 v235, v176, v177, v235
	v_max3_f32 v230, v230, v234, v235
	v_max_f32_e32 v234, v182, v183
	v_max_f32_e32 v236, v186, v186
	v_max_f32_e32 v235, v236, v187
	v_max3_f32 v234, v180, v181, v234
	v_max3_f32 v235, v184, v185, v235
	v_max3_f32 v230, v230, v234, v235
	v_mov_b32_e32 v234, v230
	s_nop 1
	v_permlane16_swap_b32_e32 v230, v234
	v_max_f32_e32 v230, v230, v234
	v_mov_b32_e32 v234, v230
	s_nop 1
	v_permlane32_swap_b32_e32 v230, v234
	v_max3_f32 v230, v208, v230, v234
	v_exp_f32_e64 v208, -v230
	s_nop 0
	v_cmp_neq_f32_e32 vcc, 1.0, v208
	s_cbranch_vccz .LBB0_572
	v_pk_mul_f32 v[82:83], v[82:83], v[208:209] op_sel_hi:[1,0]
	v_pk_mul_f32 v[80:81], v[80:81], v[208:209] op_sel_hi:[1,0]
	v_pk_mul_f32 v[78:79], v[78:79], v[208:209] op_sel_hi:[1,0]
	v_pk_mul_f32 v[76:77], v[76:77], v[208:209] op_sel_hi:[1,0]
	v_pk_mul_f32 v[74:75], v[74:75], v[208:209] op_sel_hi:[1,0]
	v_pk_mul_f32 v[72:73], v[72:73], v[208:209] op_sel_hi:[1,0]
	v_pk_mul_f32 v[70:71], v[70:71], v[208:209] op_sel_hi:[1,0]
	v_pk_mul_f32 v[68:69], v[68:69], v[208:209] op_sel_hi:[1,0]
	v_pk_mul_f32 v[66:67], v[66:67], v[208:209] op_sel_hi:[1,0]
	v_pk_mul_f32 v[64:65], v[64:65], v[208:209] op_sel_hi:[1,0]
	v_pk_mul_f32 v[62:63], v[62:63], v[208:209] op_sel_hi:[1,0]
	v_pk_mul_f32 v[60:61], v[60:61], v[208:209] op_sel_hi:[1,0]
	v_pk_mul_f32 v[54:55], v[54:55], v[208:209] op_sel_hi:[1,0]
	v_pk_mul_f32 v[52:53], v[52:53], v[208:209] op_sel_hi:[1,0]
	v_pk_mul_f32 v[58:59], v[58:59], v[208:209] op_sel_hi:[1,0]
	v_pk_mul_f32 v[56:57], v[56:57], v[208:209] op_sel_hi:[1,0]
	v_sub_f32_e32 v251, v251, v230
	v_sub_f32_e32 v172, v172, v230
	v_sub_f32_e32 v173, v173, v230
	v_sub_f32_e32 v174, v174, v230
	v_sub_f32_e32 v175, v175, v230
	v_sub_f32_e32 v176, v176, v230
	v_sub_f32_e32 v177, v177, v230
	v_sub_f32_e32 v178, v178, v230
	v_sub_f32_e32 v179, v179, v230
	v_sub_f32_e32 v180, v180, v230
	v_sub_f32_e32 v181, v181, v230
	v_sub_f32_e32 v182, v182, v230
	v_sub_f32_e32 v183, v183, v230
	v_sub_f32_e32 v184, v184, v230
	v_sub_f32_e32 v185, v185, v230
	v_sub_f32_e32 v186, v186, v230
	v_sub_f32_e32 v187, v187, v230
.LBB0_572:
	v_exp_f32_e32 v234, v164
	v_exp_f32_e32 v235, v165
	v_exp_f32_e32 v236, v166
	v_exp_f32_e32 v237, v167
	v_exp_f32_e32 v238, v168
	v_exp_f32_e32 v239, v169
	v_exp_f32_e32 v240, v170
	v_exp_f32_e32 v241, v171
	v_exp_f32_e32 v242, v190
	v_exp_f32_e32 v243, v191
	v_exp_f32_e32 v190, v188
	v_exp_f32_e32 v191, v189
	v_exp_f32_e32 v192, v192
	v_exp_f32_e32 v193, v193
	v_exp_f32_e32 v194, v194
	v_exp_f32_e32 v195, v195
	v_exp_f32_e32 v172, v172
	v_exp_f32_e32 v173, v173
	v_exp_f32_e32 v174, v174
	v_exp_f32_e32 v175, v175
	v_exp_f32_e32 v176, v176
	v_exp_f32_e32 v177, v177
	v_exp_f32_e32 v178, v178
	v_exp_f32_e32 v179, v179
	v_exp_f32_e32 v180, v180
	v_exp_f32_e32 v181, v181
	v_exp_f32_e32 v182, v182
	v_exp_f32_e32 v183, v183
	v_exp_f32_e32 v184, v184
	v_exp_f32_e32 v185, v185
	v_exp_f32_e32 v186, v186
	v_exp_f32_e32 v187, v187
	v_cvt_pk_bf16_f32 v168, v234, v235
	v_cvt_pk_bf16_f32 v169, v236, v237
	v_cvt_pk_bf16_f32 v164, v190, v191
	v_cvt_pk_bf16_f32 v166, v192, v193
	v_pk_add_f32 v[234:235], v[234:235], v[238:239]
	v_pk_add_f32 v[236:237], v[236:237], v[240:241]
	v_pk_add_f32 v[190:191], v[190:191], v[192:193]
	v_pk_add_f32 v[192:193], v[242:243], v[194:195]
	v_pk_add_f32 v[188:189], v[172:173], v[176:177]
	v_pk_add_f32 v[244:245], v[174:175], v[178:179]
	v_pk_add_f32 v[246:247], v[180:181], v[184:185]
	v_pk_add_f32 v[248:249], v[182:183], v[186:187]
	v_pk_add_f32 v[192:193], v[236:237], v[192:193]
	v_pk_add_f32 v[190:191], v[234:235], v[190:191]
	v_cvt_pk_bf16_f32 v167, v194, v195
	v_pk_add_f32 v[244:245], v[244:245], v[248:249]
	v_pk_add_f32 v[188:189], v[188:189], v[246:247]
	v_mov_b32_e32 v246, v250
	v_mov_b32_e32 v247, v250
	v_mov_b32_e32 v248, v250
	v_mov_b32_e32 v249, v250
	v_pk_mov_b32 v[194:195], v[190:191], v[192:193] op_sel:[1,0]
	v_mov_b32_e32 v191, v193
	v_add_f32_e32 v188, v188, v189
	v_add_f32_e32 v189, v244, v245
	v_pk_add_f32 v[190:191], v[194:195], v[190:191]
	v_cvt_pk_bf16_f32 v170, v238, v239
	v_cvt_pk_bf16_f32 v171, v240, v241
	v_add_f32_e32 v188, v188, v189
	v_add_f32_e32 v189, v190, v191
	v_cvt_pk_bf16_f32 v190, v172, v173
	v_cvt_pk_bf16_f32 v191, v174, v175
	v_cvt_pk_bf16_f32 v192, v176, v177
	v_cvt_pk_bf16_f32 v193, v178, v179
	s_waitcnt lgkmcnt(14)
	v_mfma_f32_16x16x32_bf16 v[4:7], v[160:163], v[168:171], v[4:7]
	v_cvt_pk_bf16_f32 v165, v242, v243
	v_cvt_pk_bf16_f32 v172, v180, v181
	v_cvt_pk_bf16_f32 v173, v182, v183
	v_mfma_f32_16x16x32_bf16 v[80:83], v[160:163], v[190:193], v[80:83]
	v_cvt_pk_bf16_f32 v174, v184, v185
	v_cvt_pk_bf16_f32 v175, v186, v187
	s_and_b32 s6, s4, 0x8000
	v_mfma_f32_16x16x32_bf16 v[8:11], v[156:159], v[168:171], v[8:11]
	s_add_i32 s6, s6, 0
	s_add_u32 s0, s0, 0x10000
	s_addc_u32 s1, s1, 0
	v_mfma_f32_16x16x32_bf16 v[76:79], v[156:159], v[190:193], v[76:79]
	s_add_i32 s4, s4, 0x8000
	v_fmac_f32_e32 v188, v233, v208
	v_fmac_f32_e32 v189, v232, v2
	v_mfma_f32_16x16x32_bf16 v[12:15], v[152:155], v[168:171], v[12:15]
	s_cmp_eq_u32 s5, s0
	v_add_u32_e32 v2, s6, v229
	v_mfma_f32_16x16x32_bf16 v[72:75], v[152:155], v[190:193], v[72:75]
	v_mfma_f32_16x16x32_bf16 v[16:19], v[148:151], v[168:171], v[16:19]
	v_mfma_f32_16x16x32_bf16 v[68:71], v[148:151], v[190:193], v[68:71]
	v_mfma_f32_16x16x32_bf16 v[20:23], v[144:147], v[168:171], v[20:23]
	v_mfma_f32_16x16x32_bf16 v[64:67], v[144:147], v[190:193], v[64:67]
	s_waitcnt lgkmcnt(10)
	v_mfma_f32_16x16x32_bf16 v[24:27], v[140:143], v[168:171], v[24:27]
	v_mfma_f32_16x16x32_bf16 v[60:63], v[140:143], v[190:193], v[60:63]
	s_waitcnt lgkmcnt(6)
	v_mfma_f32_16x16x32_bf16 v[28:31], v[136:139], v[168:171], v[28:31]
	v_mfma_f32_16x16x32_bf16 v[52:55], v[136:139], v[190:193], v[52:55]
	s_waitcnt lgkmcnt(2)
	v_mfma_f32_16x16x32_bf16 v[32:35], v[132:135], v[168:171], v[32:35]
	v_mfma_f32_16x16x32_bf16 v[56:59], v[132:135], v[190:193], v[56:59]
	v_mfma_f32_16x16x32_bf16 v[4:7], v[116:119], v[164:167], v[4:7]
	v_mfma_f32_16x16x32_bf16 v[80:83], v[116:119], v[172:175], v[80:83]
	v_mfma_f32_16x16x32_bf16 v[8:11], v[120:123], v[164:167], v[8:11]
	v_mfma_f32_16x16x32_bf16 v[76:79], v[120:123], v[172:175], v[76:79]
	v_mfma_f32_16x16x32_bf16 v[12:15], v[124:127], v[164:167], v[12:15]
	v_mfma_f32_16x16x32_bf16 v[72:75], v[124:127], v[172:175], v[72:75]
	v_mfma_f32_16x16x32_bf16 v[16:19], v[128:131], v[164:167], v[16:19]
	v_mfma_f32_16x16x32_bf16 v[68:71], v[128:131], v[172:175], v[68:71]
	v_mfma_f32_16x16x32_bf16 v[20:23], v[112:115], v[164:167], v[20:23]
	v_mfma_f32_16x16x32_bf16 v[64:67], v[112:115], v[172:175], v[64:67]
	v_mfma_f32_16x16x32_bf16 v[24:27], v[108:111], v[164:167], v[24:27]
	v_mfma_f32_16x16x32_bf16 v[60:63], v[108:111], v[172:175], v[60:63]
	v_mfma_f32_16x16x32_bf16 v[28:31], v[104:107], v[164:167], v[28:31]
	v_mfma_f32_16x16x32_bf16 v[52:55], v[104:107], v[172:175], v[52:55]
	s_waitcnt lgkmcnt(0)
	v_mfma_f32_16x16x32_bf16 v[32:35], v[100:103], v[164:167], v[32:35]
	v_mfma_f32_16x16x32_bf16 v[56:59], v[100:103], v[172:175], v[56:59]
	v_add_u32_e32 v100, s6, v228
	s_waitcnt vmcnt(3)
	ds_write_b128 v100, v[84:87]
	s_waitcnt vmcnt(2)
	ds_write_b128 v100, v[88:91] offset:8192
	s_waitcnt vmcnt(1)
	ds_write_b128 v2, v[92:95] offset:16384
	s_waitcnt vmcnt(0)
	ds_write_b128 v2, v[96:99] offset:24576
	s_waitcnt lgkmcnt(0)
	s_barrier
	s_cbranch_scc1 .LBB0_574
	v_mov_b32_e32 v232, v189
	v_mov_b32_e32 v233, v188
	v_mov_b32_e32 v208, 0
	v_mov_b32_e32 v231, 0
	s_branch .LBB0_568
.LBB0_574:
	v_sub_f32_e32 v231, 0, v250
	v_sub_f32_e32 v230, 0, v251
	v_add_u32_e32 v2, s6, v221
	ds_read_b128 v[84:87], v2
	ds_read_b128 v[88:91], v2 offset:4096
	v_add_u32_e32 v112, s6, v219
	ds_read_b128 v[92:95], v112
	ds_read_b128 v[96:99], v112 offset:4096
	v_add_u32_e32 v134, s6, v220
	s_waitcnt lgkmcnt(1)
	v_mfma_f32_16x16x32_bf16 v[92:95], v[92:95], v[44:47], 0
	s_or_b32 s94, s5, 0x10000
	v_lshl_add_u64 v[130:131], v[204:205], 0, s[94:95]
	v_lshl_add_u64 v[128:129], v[202:203], 0, s[94:95]
	v_mfma_f32_16x16x32_bf16 v[100:103], v[88:91], v[48:51], 0
	ds_read_b128 v[88:91], v2 offset:8192
	ds_read_b128 v[104:107], v2 offset:12288
	v_add_u32_e32 v2, s6, v227
	ds_read_b128 v[120:123], v134
	s_waitcnt lgkmcnt(2)
	v_mfma_f32_16x16x32_bf16 v[108:111], v[88:91], v[48:51], 0
	ds_read_b128 v[88:91], v112 offset:8192
	ds_read_b128 v[112:115], v112 offset:12288
	ds_read_b128 v[124:127], v134 offset:4096
	v_mfma_f32_16x16x32_bf16 v[84:87], v[84:87], v[48:51], 0
	v_add_co_u32_e32 v132, vcc, 0x8000, v130
	v_cmp_gt_i32_e64 s[0:1], v201, v200
	s_waitcnt lgkmcnt(2)
	v_mfma_f32_16x16x32_bf16 v[116:119], v[88:91], v[44:47], 0
	ds_read_b128 v[88:91], v2
	v_addc_co_u32_e32 v133, vcc, 0, v131, vcc
	s_waitcnt lgkmcnt(2)
	v_mfma_f32_16x16x32_bf16 v[176:179], v[112:115], v[44:47], 0
	ds_read_b128 v[112:115], v2 offset:4096
	v_cmp_lt_i32_e64 s[36:37], v201, v200
	v_add_u32_e32 v204, s6, v211
	s_waitcnt lgkmcnt(1)
	v_mfma_f32_16x16x32_bf16 v[156:159], v[88:91], v[36:39], v[84:87]
	global_load_dwordx4 v[88:91], v[130:131], off
	s_nop 1
	global_load_dwordx4 v[84:87], v[128:129], off
	v_mfma_f32_16x16x32_bf16 v[164:167], v[120:123], v[40:43], v[92:95]
	v_add_co_u32_e32 v120, vcc, 0x8000, v128
	s_nop 1
	v_cndmask_b32_e64 v192, v210, v157, s[36:37]
	ds_read_b128 v[92:95], v2 offset:8192
	v_mfma_f32_16x16x32_bf16 v[96:99], v[96:99], v[44:47], 0
	v_addc_co_u32_e32 v121, vcc, 0, v129, vcc
	s_waitcnt lgkmcnt(1)
	v_mfma_f32_16x16x32_bf16 v[160:163], v[112:115], v[36:39], v[100:103]
	ds_read_b128 v[112:115], v2 offset:12288
	v_add_u32_e32 v2, s6, v218
	s_nop 0
	ds_read_b128 v[100:103], v134 offset:8192
	v_mfma_f32_16x16x32_bf16 v[168:171], v[124:127], v[40:43], v[96:99]
	s_waitcnt lgkmcnt(2)
	v_mfma_f32_16x16x32_bf16 v[184:187], v[92:95], v[36:39], v[108:111]
	global_load_dwordx4 v[92:95], v[132:133], off
	global_load_dwordx4 v[96:99], v[120:121], off
	ds_read_b128 v[232:235], v134 offset:12288
	s_waitcnt lgkmcnt(1)
	v_mfma_f32_16x16x32_bf16 v[172:175], v[100:103], v[40:43], v[116:119]
	ds_read_b64_tr_b16 v[148:149], v2 offset:16384
	ds_read_b64_tr_b16 v[150:151], v2 offset:20480
	ds_read_b64_tr_b16 v[100:101], v2 offset:24576
	ds_read_b64_tr_b16 v[102:103], v2 offset:28672
	v_add_u32_e32 v2, s6, v217
	ds_read_b64_tr_b16 v[152:153], v2 offset:16384
	ds_read_b64_tr_b16 v[154:155], v2 offset:20480
	ds_read_b64_tr_b16 v[108:109], v2 offset:24576
	ds_read_b64_tr_b16 v[110:111], v2 offset:28672
	v_mfma_f32_16x16x32_bf16 v[104:107], v[104:107], v[48:51], 0
	v_add_u32_e32 v2, s6, v216
	ds_read_b64_tr_b16 v[144:145], v2 offset:16384
	ds_read_b64_tr_b16 v[146:147], v2 offset:20480
	ds_read_b64_tr_b16 v[116:117], v2 offset:24576
	ds_read_b64_tr_b16 v[118:119], v2 offset:28672
	v_add_u32_e32 v2, s6, v215
	ds_read_b64_tr_b16 v[140:141], v2 offset:16384
	ds_read_b64_tr_b16 v[142:143], v2 offset:20480
	ds_read_b64_tr_b16 v[124:125], v2 offset:24576
	ds_read_b64_tr_b16 v[126:127], v2 offset:28672
	v_add_u32_e32 v2, s6, v214
	ds_read_b64_tr_b16 v[136:137], v2 offset:16384
	ds_read_b64_tr_b16 v[138:139], v2 offset:20480
	ds_read_b64_tr_b16 v[120:121], v2 offset:24576
	ds_read_b64_tr_b16 v[122:123], v2 offset:28672
	v_add_u32_e32 v2, s6, v213
	v_mfma_f32_16x16x32_bf16 v[236:239], v[112:115], v[36:39], v[104:107]
	ds_read_b64_tr_b16 v[132:133], v2 offset:16384
	ds_read_b64_tr_b16 v[134:135], v2 offset:20480
	ds_read_b64_tr_b16 v[112:113], v2 offset:24576
	ds_read_b64_tr_b16 v[114:115], v2 offset:28672
	v_add_u32_e32 v2, s6, v212
	ds_read_b64_tr_b16 v[128:129], v2 offset:16384
	ds_read_b64_tr_b16 v[130:131], v2 offset:20480
	ds_read_b64_tr_b16 v[104:105], v2 offset:24576
	ds_read_b64_tr_b16 v[106:107], v2 offset:28672
	v_mov_b32_e32 v2, s46
	v_cndmask_b32_e64 v2, v156, v2, s[0:1]
	v_cndmask_b32_e64 v191, v2, v156, s[36:37]
	v_or_b32_e32 v2, 2, v201
	v_cmp_gt_i32_e64 s[4:5], v2, v200
	v_or_b32_e32 v2, 3, v201
	v_or_b32_e32 v156, 16, v201
	v_cmp_gt_i32_e64 s[6:7], v2, v200
	v_mov_b32_e32 v2, s46
	v_cmp_gt_i32_e64 s[8:9], v156, v200
	v_or_b32_e32 v156, 32, v201
	v_cmp_gt_i32_e64 s[18:19], v156, v200
	v_cndmask_b32_e64 v193, v160, v2, s[8:9]
	v_or_b32_e32 v2, 17, v201
	v_cmp_gt_i32_e64 s[10:11], v2, v200
	v_or_b32_e32 v2, 18, v201
	v_cmp_gt_i32_e64 s[12:13], v2, v200
	v_or_b32_e32 v2, 19, v201
	v_cmp_gt_i32_e64 s[14:15], v2, v200
	v_mov_b32_e32 v2, s46
	v_cndmask_b32_e64 v182, v184, v2, s[18:19]
	v_or_b32_e32 v2, 33, v201
	v_cmp_gt_i32_e64 s[20:21], v2, v200
	v_or_b32_e32 v2, 34, v201
	v_cmp_gt_i32_e64 s[22:23], v2, v200
	v_or_b32_e32 v2, 35, v201
	v_or_b32_e32 v156, 48, v201
	v_cmp_gt_i32_e64 s[24:25], v2, v200
	v_mov_b32_e32 v2, s46
	v_cmp_gt_i32_e64 s[26:27], v156, v200
	v_cndmask_b32_e64 v194, v158, v210, s[4:5]
	v_cndmask_b32_e64 v202, v159, v210, s[6:7]
	v_cndmask_b32_e64 v181, v236, v2, s[26:27]
	v_or_b32_e32 v2, 49, v201
	v_cmp_gt_i32_e64 s[28:29], v2, v200
	v_or_b32_e32 v2, 50, v201
	v_cmp_gt_i32_e64 s[30:31], v2, v200
	v_or_b32_e32 v2, 51, v201
	v_cmp_gt_i32_e64 s[34:35], v2, v200
	v_max_f32_e32 v2, v191, v191
	v_max_f32_e32 v156, v192, v192
	v_cndmask_b32_e64 v203, v162, v210, s[12:13]
	v_cndmask_b32_e64 v205, v163, v210, s[14:15]
	v_max_f32_e32 v2, v2, v156
	v_max_f32_e32 v156, v202, v202
	v_max_f32_e32 v157, v194, v194
	v_max_f32_e32 v156, v157, v156
	v_max_f32_e32 v157, v205, v205
	v_max_f32_e32 v158, v203, v203
	v_cndmask_b32_e64 v195, v161, v210, s[10:11]
	v_max_f32_e32 v157, v158, v157
	v_cndmask_b32_e64 v184, v185, v210, s[20:21]
	v_cndmask_b32_e64 v185, v186, v210, s[22:23]
	v_cndmask_b32_e64 v190, v187, v210, s[24:25]
	v_max3_f32 v157, v193, v195, v157
	v_cndmask_b32_e64 v186, v238, v210, s[30:31]
	v_cndmask_b32_e64 v187, v239, v210, s[34:35]
	v_max3_f32 v2, v2, v156, v157
	v_max_f32_e32 v156, v190, v190
	v_max_f32_e32 v157, v185, v185
	v_max_f32_e32 v156, v157, v156
	v_max_f32_e32 v157, v187, v187
	v_max_f32_e32 v158, v186, v186
	v_cndmask_b32_e64 v183, v237, v210, s[28:29]
	v_max_f32_e32 v157, v158, v157
	v_max3_f32 v156, v182, v184, v156
	v_max3_f32 v157, v181, v183, v157
	v_max3_f32 v2, v2, v156, v157
	v_mov_b32_e32 v156, v2
	s_nop 1
	v_permlane16_swap_b32_e32 v2, v156
	v_max_f32_e32 v156, v156, v156
	v_max_f32_e32 v2, v2, v2
	v_max_f32_e32 v2, v2, v156
	v_mov_b32_e32 v156, v2
	s_nop 1
	v_permlane32_swap_b32_e32 v2, v156
	v_max3_f32 v180, v231, v2, v156
	ds_read_b64_tr_b16 v[160:161], v204 offset:16384
	ds_read_b64_tr_b16 v[162:163], v204 offset:20480
	ds_read_b64_tr_b16 v[156:157], v204 offset:24576
	ds_read_b64_tr_b16 v[158:159], v204 offset:28672
	v_sub_f32_e32 v2, v231, v180
	v_exp_f32_e32 v2, v2
	s_waitcnt lgkmcnt(14)
	v_mfma_f32_16x16x32_bf16 v[176:179], v[232:235], v[40:43], v[176:179]
	v_cmp_neq_f32_e32 vcc, 1.0, v2
	s_cbranch_vccz .LBB0_576
	v_pk_mul_f32 v[34:35], v[34:35], v[2:3] op_sel_hi:[1,0]
	v_pk_mul_f32 v[30:31], v[30:31], v[2:3] op_sel_hi:[1,0]
	v_pk_mul_f32 v[26:27], v[26:27], v[2:3] op_sel_hi:[1,0]
	v_pk_mul_f32 v[22:23], v[22:23], v[2:3] op_sel_hi:[1,0]
	v_pk_mul_f32 v[18:19], v[18:19], v[2:3] op_sel_hi:[1,0]
	v_pk_mul_f32 v[14:15], v[14:15], v[2:3] op_sel_hi:[1,0]
	v_pk_mul_f32 v[10:11], v[10:11], v[2:3] op_sel_hi:[1,0]
	v_pk_mul_f32 v[6:7], v[6:7], v[2:3] op_sel_hi:[1,0]
	v_pk_mul_f32 v[32:33], v[32:33], v[2:3] op_sel_hi:[1,0]
	v_pk_mul_f32 v[28:29], v[28:29], v[2:3] op_sel_hi:[1,0]
	v_pk_mul_f32 v[24:25], v[24:25], v[2:3] op_sel_hi:[1,0]
	v_pk_mul_f32 v[20:21], v[20:21], v[2:3] op_sel_hi:[1,0]
	v_pk_mul_f32 v[16:17], v[16:17], v[2:3] op_sel_hi:[1,0]
	v_pk_mul_f32 v[12:13], v[12:13], v[2:3] op_sel_hi:[1,0]
	v_pk_mul_f32 v[8:9], v[8:9], v[2:3] op_sel_hi:[1,0]
	v_pk_mul_f32 v[4:5], v[4:5], v[2:3] op_sel_hi:[1,0]
